# v10 + removed the mid-block s_setprio 0/1 flip inside each 32-MFMA block of the GEMM K-loops (24 sites)
# speedup vs baseline: 1.0050x; 1.0050x over previous
.LBB0_180:
	s_add_u32 s12, s26, s8
	s_addc_u32 s13, s27, s9
	s_add_u32 s12, s12, 0x100
	s_addc_u32 s13, s13, 0
	s_add_u32 s81, s67, s8
	s_addc_u32 s83, s43, s9
	s_add_i32 s95, 0, 0x10000
	s_cmpk_eq_i32 s8, 0xf00
	s_cselect_b32 s35, s25, s13
	s_cselect_b32 s34, s36, s12
	s_cselect_b32 s13, s23, s83
	s_cselect_b32 s12, s37, s81
	s_add_i32 s81, 0, 0x14000
	v_add_u32_e32 v148, s95, v230
	v_add_u32_e32 v164, s81, v230
	ds_read_b128 v[136:139], v148
	ds_read_b128 v[140:143], v148 offset:1024
	ds_read_b128 v[144:147], v148 offset:2048
	ds_read_b128 v[148:151], v148 offset:3072
	ds_read_b128 v[152:155], v164
	ds_read_b128 v[156:159], v164 offset:1024
	ds_read_b128 v[160:163], v164 offset:2048
	ds_read_b128 v[164:167], v164 offset:3072
	v_lshl_add_u64 v[196:197], v[132:133], 0, s[8:9]
	s_add_i32 m0, s39, 0xc000
	ds_read_b128 v[168:171], v242
	ds_read_b128 v[188:191], v242 offset:1024
	ds_read_b128 v[192:195], v242 offset:2048
	ds_read_b128 v[204:207], v242 offset:3072
	ds_read_b128 v[208:211], v242 offset:4096
	ds_read_b128 v[212:215], v242 offset:5120
	ds_read_b128 v[244:247], v242 offset:6144
	ds_read_b128 v[248:251], v242 offset:7168
	global_load_lds_dwordx4 v[196:197], off
	v_lshl_add_u64 v[196:197], v[134:135], 0, s[8:9]
	s_add_i32 m0, s39, 0xe000
	s_nop 0
	global_load_lds_dwordx4 v[196:197], off
	s_waitcnt vmcnt(8)
	s_waitcnt lgkmcnt(0)
	s_setprio 1
	s_barrier
	v_mfma_f32_16x16x32_bf16 v[8:11], v[136:139], v[168:171], v[8:11]
	v_mfma_f32_16x16x32_bf16 v[128:131], v[144:147], v[168:171], v[128:131]
	v_mfma_f32_16x16x32_bf16 v[124:127], v[136:139], v[192:195], v[124:127]
	v_mfma_f32_16x16x32_bf16 v[120:123], v[144:147], v[192:195], v[120:123]
	v_mfma_f32_16x16x32_bf16 v[116:119], v[136:139], v[208:211], v[116:119]
	v_mfma_f32_16x16x32_bf16 v[112:115], v[144:147], v[208:211], v[112:115]
	v_mfma_f32_16x16x32_bf16 v[108:111], v[136:139], v[244:247], v[108:111]
	v_mfma_f32_16x16x32_bf16 v[104:107], v[144:147], v[244:247], v[104:107]
	v_mfma_f32_16x16x32_bf16 v[8:11], v[140:143], v[188:191], v[8:11]
	v_mfma_f32_16x16x32_bf16 v[128:131], v[148:151], v[188:191], v[128:131]
	v_mfma_f32_16x16x32_bf16 v[124:127], v[140:143], v[204:207], v[124:127]
	v_mfma_f32_16x16x32_bf16 v[120:123], v[148:151], v[204:207], v[120:123]
	v_mfma_f32_16x16x32_bf16 v[116:119], v[140:143], v[212:215], v[116:119]
	v_mfma_f32_16x16x32_bf16 v[112:115], v[148:151], v[212:215], v[112:115]
	v_mfma_f32_16x16x32_bf16 v[108:111], v[140:143], v[248:251], v[108:111]
	v_mfma_f32_16x16x32_bf16 v[104:107], v[148:151], v[248:251], v[104:107]
	v_mfma_f32_16x16x32_bf16 v[100:103], v[152:155], v[168:171], v[100:103]
	v_mfma_f32_16x16x32_bf16 v[96:99], v[160:163], v[168:171], v[96:99]
	v_mfma_f32_16x16x32_bf16 v[92:95], v[152:155], v[192:195], v[92:95]
	v_mfma_f32_16x16x32_bf16 v[88:91], v[160:163], v[192:195], v[88:91]
	v_mfma_f32_16x16x32_bf16 v[84:87], v[152:155], v[208:211], v[84:87]
	v_mfma_f32_16x16x32_bf16 v[80:83], v[160:163], v[208:211], v[80:83]
	v_mfma_f32_16x16x32_bf16 v[76:79], v[152:155], v[244:247], v[76:79]
	v_mfma_f32_16x16x32_bf16 v[72:75], v[160:163], v[244:247], v[72:75]
	v_mfma_f32_16x16x32_bf16 v[100:103], v[156:159], v[188:191], v[100:103]
	v_mfma_f32_16x16x32_bf16 v[96:99], v[164:167], v[188:191], v[96:99]
	v_mfma_f32_16x16x32_bf16 v[92:95], v[156:159], v[204:207], v[92:95]
	v_mfma_f32_16x16x32_bf16 v[88:91], v[164:167], v[204:207], v[88:91]
	v_mfma_f32_16x16x32_bf16 v[84:87], v[156:159], v[212:215], v[84:87]
	v_mfma_f32_16x16x32_bf16 v[80:83], v[164:167], v[212:215], v[80:83]
	v_mfma_f32_16x16x32_bf16 v[76:79], v[156:159], v[248:251], v[76:79]
	v_mfma_f32_16x16x32_bf16 v[72:75], v[164:167], v[248:251], v[72:75]
	s_setprio 0
	s_barrier
	s_add_i32 s83, s95, s38
	v_lshl_add_u64 v[196:197], s[12:13], 0, v[172:173]
	s_mov_b32 m0, s83
	ds_read_b128 v[168:171], v242 offset:16384
	ds_read_b128 v[188:191], v242 offset:17408
	ds_read_b128 v[192:195], v242 offset:18432
	ds_read_b128 v[204:207], v242 offset:19456
	ds_read_b128 v[208:211], v242 offset:20480
	ds_read_b128 v[212:215], v242 offset:21504
	ds_read_b128 v[244:247], v242 offset:22528
	ds_read_b128 v[248:251], v242 offset:23552
	global_load_lds_dwordx4 v[196:197], off
	s_add_i32 m0, s83, 0x2000
	s_add_u32 vcc_lo, s12, 0x80000
	v_lshl_add_u64 v[198:199], s[12:13], 0, v[176:177]
	s_addc_u32 vcc_hi, s13, 0
	s_add_i32 s81, s81, s38
	global_load_lds_dwordx4 v[198:199], off
	v_lshl_add_u64 v[200:201], vcc, 0, v[172:173]
	s_mov_b32 m0, s81
	v_lshl_add_u64 v[202:203], s[34:35], 0, v[174:175]
	global_load_lds_dwordx4 v[200:201], off
	v_lshl_add_u64 v[200:201], vcc, 0, v[176:177]
	s_add_i32 m0, s81, 0x2000
	s_nop 0
	global_load_lds_dwordx4 v[200:201], off
	v_lshl_add_u64 v[200:201], s[34:35], 0, v[0:1]
	s_mov_b32 m0, s39
	s_nop 0
	global_load_lds_dwordx4 v[200:201], off
	s_mov_b32 m0, s46
	s_nop 0
	global_load_lds_dwordx4 v[202:203], off
	s_waitcnt vmcnt(8)
	s_waitcnt lgkmcnt(0)
	s_setprio 1
	s_barrier
	v_mfma_f32_16x16x32_bf16 v[68:71], v[136:139], v[168:171], v[68:71]
	v_mfma_f32_16x16x32_bf16 v[64:67], v[144:147], v[168:171], v[64:67]
	v_mfma_f32_16x16x32_bf16 v[60:63], v[136:139], v[192:195], v[60:63]
	v_mfma_f32_16x16x32_bf16 v[56:59], v[144:147], v[192:195], v[56:59]
	v_mfma_f32_16x16x32_bf16 v[52:55], v[136:139], v[208:211], v[52:55]
	v_mfma_f32_16x16x32_bf16 v[48:51], v[144:147], v[208:211], v[48:51]
	v_mfma_f32_16x16x32_bf16 v[44:47], v[136:139], v[244:247], v[44:47]
	v_mfma_f32_16x16x32_bf16 v[40:43], v[144:147], v[244:247], v[40:43]
	v_mfma_f32_16x16x32_bf16 v[68:71], v[140:143], v[188:191], v[68:71]
	v_mfma_f32_16x16x32_bf16 v[64:67], v[148:151], v[188:191], v[64:67]
	v_mfma_f32_16x16x32_bf16 v[60:63], v[140:143], v[204:207], v[60:63]
	v_mfma_f32_16x16x32_bf16 v[56:59], v[148:151], v[204:207], v[56:59]
	v_mfma_f32_16x16x32_bf16 v[52:55], v[140:143], v[212:215], v[52:55]
	v_mfma_f32_16x16x32_bf16 v[48:51], v[148:151], v[212:215], v[48:51]
	v_mfma_f32_16x16x32_bf16 v[44:47], v[140:143], v[248:251], v[44:47]
	v_mfma_f32_16x16x32_bf16 v[40:43], v[148:151], v[248:251], v[40:43]
	v_mfma_f32_16x16x32_bf16 v[36:39], v[152:155], v[168:171], v[36:39]
	v_mfma_f32_16x16x32_bf16 v[32:35], v[160:163], v[168:171], v[32:35]
	v_mfma_f32_16x16x32_bf16 v[28:31], v[152:155], v[192:195], v[28:31]
	v_mfma_f32_16x16x32_bf16 v[24:27], v[160:163], v[192:195], v[24:27]
	v_mfma_f32_16x16x32_bf16 v[20:23], v[152:155], v[208:211], v[20:23]
	v_mfma_f32_16x16x32_bf16 v[16:19], v[160:163], v[208:211], v[16:19]
	v_mfma_f32_16x16x32_bf16 v[12:15], v[152:155], v[244:247], v[12:15]
	v_mfma_f32_16x16x32_bf16 v[4:7], v[160:163], v[244:247], v[4:7]
	v_mfma_f32_16x16x32_bf16 v[36:39], v[156:159], v[188:191], v[36:39]
	v_mfma_f32_16x16x32_bf16 v[32:35], v[164:167], v[188:191], v[32:35]
	v_mfma_f32_16x16x32_bf16 v[28:31], v[156:159], v[204:207], v[28:31]
	v_mfma_f32_16x16x32_bf16 v[24:27], v[164:167], v[204:207], v[24:27]
	v_mfma_f32_16x16x32_bf16 v[20:23], v[156:159], v[212:215], v[20:23]
	v_mfma_f32_16x16x32_bf16 v[16:19], v[164:167], v[212:215], v[16:19]
	v_mfma_f32_16x16x32_bf16 v[12:15], v[156:159], v[248:251], v[12:15]
	v_mfma_f32_16x16x32_bf16 v[4:7], v[164:167], v[248:251], v[4:7]
	s_setprio 0
	s_barrier
	s_add_i32 s81, 0, 0x18000
	s_add_i32 s83, 0, 0x1c000
	v_add_u32_e32 v148, s81, v230
	v_add_u32_e32 v164, s83, v230
	ds_read_b128 v[136:139], v148
	ds_read_b128 v[140:143], v148 offset:1024
	ds_read_b128 v[144:147], v148 offset:2048
	ds_read_b128 v[148:151], v148 offset:3072
	ds_read_b128 v[152:155], v164
	ds_read_b128 v[156:159], v164 offset:1024
	ds_read_b128 v[160:163], v164 offset:2048
	ds_read_b128 v[164:167], v164 offset:3072
	s_add_u32 s34, s34, 0x80000
	s_addc_u32 s35, s35, 0
	s_mov_b32 m0, s47
	v_lshl_add_u64 v[216:217], s[34:35], 0, v[0:1]
	ds_read_b128 v[168:171], v242 offset:32768
	ds_read_b128 v[188:191], v242 offset:33792
	ds_read_b128 v[192:195], v242 offset:34816
	ds_read_b128 v[204:207], v242 offset:35840
	ds_read_b128 v[208:211], v242 offset:36864
	ds_read_b128 v[212:215], v242 offset:37888
	ds_read_b128 v[244:247], v242 offset:38912
	ds_read_b128 v[248:251], v242 offset:39936
	global_load_lds_dwordx4 v[216:217], off
	v_lshl_add_u64 v[216:217], s[34:35], 0, v[174:175]
	s_mov_b32 m0, s51
	s_nop 0
	global_load_lds_dwordx4 v[216:217], off
	s_waitcnt vmcnt(8)
	s_waitcnt lgkmcnt(0)
	s_setprio 1
	s_barrier
	v_mfma_f32_16x16x32_bf16 v[8:11], v[136:139], v[168:171], v[8:11]
	v_mfma_f32_16x16x32_bf16 v[128:131], v[144:147], v[168:171], v[128:131]
	v_mfma_f32_16x16x32_bf16 v[124:127], v[136:139], v[192:195], v[124:127]
	v_mfma_f32_16x16x32_bf16 v[120:123], v[144:147], v[192:195], v[120:123]
	v_mfma_f32_16x16x32_bf16 v[116:119], v[136:139], v[208:211], v[116:119]
	v_mfma_f32_16x16x32_bf16 v[112:115], v[144:147], v[208:211], v[112:115]
	v_mfma_f32_16x16x32_bf16 v[108:111], v[136:139], v[244:247], v[108:111]
	v_mfma_f32_16x16x32_bf16 v[104:107], v[144:147], v[244:247], v[104:107]
	v_mfma_f32_16x16x32_bf16 v[8:11], v[140:143], v[188:191], v[8:11]
	v_mfma_f32_16x16x32_bf16 v[128:131], v[148:151], v[188:191], v[128:131]
	v_mfma_f32_16x16x32_bf16 v[124:127], v[140:143], v[204:207], v[124:127]
	v_mfma_f32_16x16x32_bf16 v[120:123], v[148:151], v[204:207], v[120:123]
	v_mfma_f32_16x16x32_bf16 v[116:119], v[140:143], v[212:215], v[116:119]
	v_mfma_f32_16x16x32_bf16 v[112:115], v[148:151], v[212:215], v[112:115]
	v_mfma_f32_16x16x32_bf16 v[108:111], v[140:143], v[248:251], v[108:111]
	v_mfma_f32_16x16x32_bf16 v[104:107], v[148:151], v[248:251], v[104:107]
	v_mfma_f32_16x16x32_bf16 v[100:103], v[152:155], v[168:171], v[100:103]
	v_mfma_f32_16x16x32_bf16 v[96:99], v[160:163], v[168:171], v[96:99]
	v_mfma_f32_16x16x32_bf16 v[92:95], v[152:155], v[192:195], v[92:95]
	v_mfma_f32_16x16x32_bf16 v[88:91], v[160:163], v[192:195], v[88:91]
	v_mfma_f32_16x16x32_bf16 v[84:87], v[152:155], v[208:211], v[84:87]
	v_mfma_f32_16x16x32_bf16 v[80:83], v[160:163], v[208:211], v[80:83]
	v_mfma_f32_16x16x32_bf16 v[76:79], v[152:155], v[244:247], v[76:79]
	v_mfma_f32_16x16x32_bf16 v[72:75], v[160:163], v[244:247], v[72:75]
	v_mfma_f32_16x16x32_bf16 v[100:103], v[156:159], v[188:191], v[100:103]
	v_mfma_f32_16x16x32_bf16 v[96:99], v[164:167], v[188:191], v[96:99]
	v_mfma_f32_16x16x32_bf16 v[92:95], v[156:159], v[204:207], v[92:95]
	v_mfma_f32_16x16x32_bf16 v[88:91], v[164:167], v[204:207], v[88:91]
	v_mfma_f32_16x16x32_bf16 v[84:87], v[156:159], v[212:215], v[84:87]
	v_mfma_f32_16x16x32_bf16 v[80:83], v[164:167], v[212:215], v[80:83]
	v_mfma_f32_16x16x32_bf16 v[76:79], v[156:159], v[248:251], v[76:79]
	v_mfma_f32_16x16x32_bf16 v[72:75], v[164:167], v[248:251], v[72:75]
	s_setprio 0
	s_barrier
	s_add_i32 s34, s81, s38
	v_lshl_add_u64 v[196:197], v[196:197], 0, s[70:71]
	s_mov_b32 m0, s34
	ds_read_b128 v[168:171], v242 offset:49152
	ds_read_b128 v[188:191], v242 offset:50176
	ds_read_b128 v[192:195], v242 offset:51200
	ds_read_b128 v[204:207], v242 offset:52224
	ds_read_b128 v[208:211], v242 offset:53248
	ds_read_b128 v[212:215], v242 offset:54272
	ds_read_b128 v[244:247], v242 offset:55296
	ds_read_b128 v[248:251], v242 offset:56320
	global_load_lds_dwordx4 v[196:197], off
	s_add_i32 m0, s34, 0x2000
	s_add_u32 s12, s12, 0x80080
	v_lshl_add_u64 v[196:197], v[198:199], 0, s[70:71]
	s_addc_u32 s13, s13, 0
	s_add_i32 s34, s83, s38
	global_load_lds_dwordx4 v[196:197], off
	v_lshl_add_u64 v[196:197], s[12:13], 0, v[172:173]
	s_mov_b32 m0, s34
	s_nop 0
	global_load_lds_dwordx4 v[196:197], off
	v_lshl_add_u64 v[196:197], s[12:13], 0, v[176:177]
	s_add_i32 m0, s34, 0x2000
	s_nop 0
	global_load_lds_dwordx4 v[196:197], off
	v_lshl_add_u64 v[196:197], v[200:201], 0, s[70:71]
	s_mov_b32 m0, s74
	s_nop 0
	global_load_lds_dwordx4 v[196:197], off
	v_lshl_add_u64 v[196:197], v[202:203], 0, s[70:71]
	s_mov_b32 m0, s75
	s_nop 0
	global_load_lds_dwordx4 v[196:197], off
	s_waitcnt vmcnt(8)
	s_waitcnt lgkmcnt(0)
	s_setprio 1
	s_barrier
	v_mfma_f32_16x16x32_bf16 v[68:71], v[136:139], v[168:171], v[68:71]
	v_mfma_f32_16x16x32_bf16 v[64:67], v[144:147], v[168:171], v[64:67]
	v_mfma_f32_16x16x32_bf16 v[60:63], v[136:139], v[192:195], v[60:63]
	v_mfma_f32_16x16x32_bf16 v[56:59], v[144:147], v[192:195], v[56:59]
	v_mfma_f32_16x16x32_bf16 v[52:55], v[136:139], v[208:211], v[52:55]
	v_mfma_f32_16x16x32_bf16 v[48:51], v[144:147], v[208:211], v[48:51]
	v_mfma_f32_16x16x32_bf16 v[44:47], v[136:139], v[244:247], v[44:47]
	v_mfma_f32_16x16x32_bf16 v[40:43], v[144:147], v[244:247], v[40:43]
	v_mfma_f32_16x16x32_bf16 v[68:71], v[140:143], v[188:191], v[68:71]
	v_mfma_f32_16x16x32_bf16 v[64:67], v[148:151], v[188:191], v[64:67]
	v_mfma_f32_16x16x32_bf16 v[60:63], v[140:143], v[204:207], v[60:63]
	v_mfma_f32_16x16x32_bf16 v[56:59], v[148:151], v[204:207], v[56:59]
	v_mfma_f32_16x16x32_bf16 v[52:55], v[140:143], v[212:215], v[52:55]
	v_mfma_f32_16x16x32_bf16 v[48:51], v[148:151], v[212:215], v[48:51]
	v_mfma_f32_16x16x32_bf16 v[44:47], v[140:143], v[248:251], v[44:47]
	v_mfma_f32_16x16x32_bf16 v[40:43], v[148:151], v[248:251], v[40:43]
	v_mfma_f32_16x16x32_bf16 v[36:39], v[152:155], v[168:171], v[36:39]
	v_mfma_f32_16x16x32_bf16 v[32:35], v[160:163], v[168:171], v[32:35]
	v_mfma_f32_16x16x32_bf16 v[28:31], v[152:155], v[192:195], v[28:31]
	v_mfma_f32_16x16x32_bf16 v[24:27], v[160:163], v[192:195], v[24:27]
	v_mfma_f32_16x16x32_bf16 v[20:23], v[152:155], v[208:211], v[20:23]
	v_mfma_f32_16x16x32_bf16 v[16:19], v[160:163], v[208:211], v[16:19]
	v_mfma_f32_16x16x32_bf16 v[12:15], v[152:155], v[244:247], v[12:15]
	v_mfma_f32_16x16x32_bf16 v[4:7], v[160:163], v[244:247], v[4:7]
	v_mfma_f32_16x16x32_bf16 v[36:39], v[156:159], v[188:191], v[36:39]
	v_mfma_f32_16x16x32_bf16 v[32:35], v[164:167], v[188:191], v[32:35]
	v_mfma_f32_16x16x32_bf16 v[28:31], v[156:159], v[204:207], v[28:31]
	v_mfma_f32_16x16x32_bf16 v[24:27], v[164:167], v[204:207], v[24:27]
	v_mfma_f32_16x16x32_bf16 v[20:23], v[156:159], v[212:215], v[20:23]
	v_mfma_f32_16x16x32_bf16 v[16:19], v[164:167], v[212:215], v[16:19]
	v_mfma_f32_16x16x32_bf16 v[12:15], v[156:159], v[248:251], v[12:15]
	v_mfma_f32_16x16x32_bf16 v[4:7], v[164:167], v[248:251], v[4:7]
	s_setprio 0
	s_barrier
	s_add_i32 s42, s42, 2
	s_add_u32 s8, s8, 0x100
	s_addc_u32 s9, s9, 0
	s_cmp_gt_u32 s42, 29
	s_cbranch_scc0 .LBB0_180
	s_and_b64 vcc, exec, s[20:21]
	s_cbranch_vccz .LBB0_183
	s_barrier

.LBB0_319:
	s_add_u32 s12, s28, s8
	s_addc_u32 s13, s29, s9
	s_add_u32 s12, s12, 0x100
	s_addc_u32 s13, s13, 0
	s_add_u32 s43, s92, s8
	s_addc_u32 s66, s93, s9
	s_add_i32 s67, 0, 0x10000
	s_cmpk_eq_i32 s8, 0xf00
	s_cselect_b32 s17, s27, s13
	s_cselect_b32 s16, s36, s12
	s_cselect_b32 s13, s25, s66
	s_cselect_b32 s12, s37, s43
	s_add_i32 s43, 0, 0x14000
	v_add_u32_e32 v148, s67, v229
	v_add_u32_e32 v164, s43, v229
	ds_read_b128 v[136:139], v148
	ds_read_b128 v[140:143], v148 offset:1024
	ds_read_b128 v[144:147], v148 offset:2048
	ds_read_b128 v[148:151], v148 offset:3072
	ds_read_b128 v[152:155], v164
	ds_read_b128 v[156:159], v164 offset:1024
	ds_read_b128 v[160:163], v164 offset:2048
	ds_read_b128 v[164:167], v164 offset:3072
	v_lshl_add_u64 v[194:195], v[132:133], 0, s[8:9]
	s_add_i32 m0, s39, 0xc000
	ds_read_b128 v[168:171], v242
	ds_read_b128 v[186:189], v242 offset:1024
	ds_read_b128 v[190:193], v242 offset:2048
	ds_read_b128 v[204:207], v242 offset:3072
	ds_read_b128 v[208:211], v242 offset:4096
	ds_read_b128 v[212:215], v242 offset:5120
	ds_read_b128 v[244:247], v242 offset:6144
	ds_read_b128 v[248:251], v242 offset:7168
	global_load_lds_dwordx4 v[194:195], off
	v_lshl_add_u64 v[194:195], v[134:135], 0, s[8:9]
	s_add_i32 m0, s39, 0xe000
	s_nop 0
	global_load_lds_dwordx4 v[194:195], off
	s_waitcnt vmcnt(8)
	s_waitcnt lgkmcnt(0)
	s_setprio 1
	s_barrier
	v_mfma_f32_16x16x32_bf16 v[8:11], v[136:139], v[168:171], v[8:11]
	v_mfma_f32_16x16x32_bf16 v[128:131], v[144:147], v[168:171], v[128:131]
	v_mfma_f32_16x16x32_bf16 v[124:127], v[136:139], v[190:193], v[124:127]
	v_mfma_f32_16x16x32_bf16 v[120:123], v[144:147], v[190:193], v[120:123]
	v_mfma_f32_16x16x32_bf16 v[116:119], v[136:139], v[208:211], v[116:119]
	v_mfma_f32_16x16x32_bf16 v[112:115], v[144:147], v[208:211], v[112:115]
	v_mfma_f32_16x16x32_bf16 v[108:111], v[136:139], v[244:247], v[108:111]
	v_mfma_f32_16x16x32_bf16 v[104:107], v[144:147], v[244:247], v[104:107]
	v_mfma_f32_16x16x32_bf16 v[8:11], v[140:143], v[186:189], v[8:11]
	v_mfma_f32_16x16x32_bf16 v[128:131], v[148:151], v[186:189], v[128:131]
	v_mfma_f32_16x16x32_bf16 v[124:127], v[140:143], v[204:207], v[124:127]
	v_mfma_f32_16x16x32_bf16 v[120:123], v[148:151], v[204:207], v[120:123]
	v_mfma_f32_16x16x32_bf16 v[116:119], v[140:143], v[212:215], v[116:119]
	v_mfma_f32_16x16x32_bf16 v[112:115], v[148:151], v[212:215], v[112:115]
	v_mfma_f32_16x16x32_bf16 v[108:111], v[140:143], v[248:251], v[108:111]
	v_mfma_f32_16x16x32_bf16 v[104:107], v[148:151], v[248:251], v[104:107]
	v_mfma_f32_16x16x32_bf16 v[100:103], v[152:155], v[168:171], v[100:103]
	v_mfma_f32_16x16x32_bf16 v[96:99], v[160:163], v[168:171], v[96:99]
	v_mfma_f32_16x16x32_bf16 v[92:95], v[152:155], v[190:193], v[92:95]
	v_mfma_f32_16x16x32_bf16 v[88:91], v[160:163], v[190:193], v[88:91]
	v_mfma_f32_16x16x32_bf16 v[84:87], v[152:155], v[208:211], v[84:87]
	v_mfma_f32_16x16x32_bf16 v[80:83], v[160:163], v[208:211], v[80:83]
	v_mfma_f32_16x16x32_bf16 v[76:79], v[152:155], v[244:247], v[76:79]
	v_mfma_f32_16x16x32_bf16 v[72:75], v[160:163], v[244:247], v[72:75]
	v_mfma_f32_16x16x32_bf16 v[100:103], v[156:159], v[186:189], v[100:103]
	v_mfma_f32_16x16x32_bf16 v[96:99], v[164:167], v[186:189], v[96:99]
	v_mfma_f32_16x16x32_bf16 v[92:95], v[156:159], v[204:207], v[92:95]
	v_mfma_f32_16x16x32_bf16 v[88:91], v[164:167], v[204:207], v[88:91]
	v_mfma_f32_16x16x32_bf16 v[84:87], v[156:159], v[212:215], v[84:87]
	v_mfma_f32_16x16x32_bf16 v[80:83], v[164:167], v[212:215], v[80:83]
	v_mfma_f32_16x16x32_bf16 v[76:79], v[156:159], v[248:251], v[76:79]
	v_mfma_f32_16x16x32_bf16 v[72:75], v[164:167], v[248:251], v[72:75]
	s_setprio 0
	s_barrier
	s_add_i32 s66, s67, s38
	v_lshl_add_u64 v[194:195], s[12:13], 0, v[172:173]
	s_mov_b32 m0, s66
	ds_read_b128 v[168:171], v242 offset:16384
	ds_read_b128 v[186:189], v242 offset:17408
	ds_read_b128 v[190:193], v242 offset:18432
	ds_read_b128 v[204:207], v242 offset:19456
	ds_read_b128 v[208:211], v242 offset:20480
	ds_read_b128 v[212:215], v242 offset:21504
	ds_read_b128 v[244:247], v242 offset:22528
	ds_read_b128 v[248:251], v242 offset:23552
	global_load_lds_dwordx4 v[194:195], off
	s_add_i32 m0, s66, 0x2000
	s_add_u32 s66, s12, 0x80000
	v_lshl_add_u64 v[196:197], s[12:13], 0, v[176:177]
	s_addc_u32 s67, s13, 0
	s_add_i32 s43, s43, s38
	global_load_lds_dwordx4 v[196:197], off
	v_lshl_add_u64 v[198:199], s[66:67], 0, v[172:173]
	s_mov_b32 m0, s43
	v_lshl_add_u64 v[200:201], s[16:17], 0, v[174:175]
	global_load_lds_dwordx4 v[198:199], off
	v_lshl_add_u64 v[198:199], s[66:67], 0, v[176:177]
	s_add_i32 m0, s43, 0x2000
	s_nop 0
	global_load_lds_dwordx4 v[198:199], off
	v_lshl_add_u64 v[198:199], s[16:17], 0, v[0:1]
	s_mov_b32 m0, s39
	s_nop 0
	global_load_lds_dwordx4 v[198:199], off
	s_mov_b32 m0, s46
	s_nop 0
	global_load_lds_dwordx4 v[200:201], off
	s_waitcnt vmcnt(8)
	s_waitcnt lgkmcnt(0)
	s_setprio 1
	s_barrier
	v_mfma_f32_16x16x32_bf16 v[68:71], v[136:139], v[168:171], v[68:71]
	v_mfma_f32_16x16x32_bf16 v[64:67], v[144:147], v[168:171], v[64:67]
	v_mfma_f32_16x16x32_bf16 v[60:63], v[136:139], v[190:193], v[60:63]
	v_mfma_f32_16x16x32_bf16 v[56:59], v[144:147], v[190:193], v[56:59]
	v_mfma_f32_16x16x32_bf16 v[52:55], v[136:139], v[208:211], v[52:55]
	v_mfma_f32_16x16x32_bf16 v[48:51], v[144:147], v[208:211], v[48:51]
	v_mfma_f32_16x16x32_bf16 v[44:47], v[136:139], v[244:247], v[44:47]
	v_mfma_f32_16x16x32_bf16 v[40:43], v[144:147], v[244:247], v[40:43]
	v_mfma_f32_16x16x32_bf16 v[68:71], v[140:143], v[186:189], v[68:71]
	v_mfma_f32_16x16x32_bf16 v[64:67], v[148:151], v[186:189], v[64:67]
	v_mfma_f32_16x16x32_bf16 v[60:63], v[140:143], v[204:207], v[60:63]
	v_mfma_f32_16x16x32_bf16 v[56:59], v[148:151], v[204:207], v[56:59]
	v_mfma_f32_16x16x32_bf16 v[52:55], v[140:143], v[212:215], v[52:55]
	v_mfma_f32_16x16x32_bf16 v[48:51], v[148:151], v[212:215], v[48:51]
	v_mfma_f32_16x16x32_bf16 v[44:47], v[140:143], v[248:251], v[44:47]
	v_mfma_f32_16x16x32_bf16 v[40:43], v[148:151], v[248:251], v[40:43]
	v_mfma_f32_16x16x32_bf16 v[36:39], v[152:155], v[168:171], v[36:39]
	v_mfma_f32_16x16x32_bf16 v[32:35], v[160:163], v[168:171], v[32:35]
	v_mfma_f32_16x16x32_bf16 v[28:31], v[152:155], v[190:193], v[28:31]
	v_mfma_f32_16x16x32_bf16 v[24:27], v[160:163], v[190:193], v[24:27]
	v_mfma_f32_16x16x32_bf16 v[20:23], v[152:155], v[208:211], v[20:23]
	v_mfma_f32_16x16x32_bf16 v[16:19], v[160:163], v[208:211], v[16:19]
	v_mfma_f32_16x16x32_bf16 v[12:15], v[152:155], v[244:247], v[12:15]
	v_mfma_f32_16x16x32_bf16 v[4:7], v[160:163], v[244:247], v[4:7]
	v_mfma_f32_16x16x32_bf16 v[36:39], v[156:159], v[186:189], v[36:39]
	v_mfma_f32_16x16x32_bf16 v[32:35], v[164:167], v[186:189], v[32:35]
	v_mfma_f32_16x16x32_bf16 v[28:31], v[156:159], v[204:207], v[28:31]
	v_mfma_f32_16x16x32_bf16 v[24:27], v[164:167], v[204:207], v[24:27]
	v_mfma_f32_16x16x32_bf16 v[20:23], v[156:159], v[212:215], v[20:23]
	v_mfma_f32_16x16x32_bf16 v[16:19], v[164:167], v[212:215], v[16:19]
	v_mfma_f32_16x16x32_bf16 v[12:15], v[156:159], v[248:251], v[12:15]
	v_mfma_f32_16x16x32_bf16 v[4:7], v[164:167], v[248:251], v[4:7]
	s_setprio 0
	s_barrier
	s_add_i32 s43, 0, 0x18000
	s_add_i32 s66, 0, 0x1c000
	v_add_u32_e32 v148, s43, v229
	v_add_u32_e32 v164, s66, v229
	ds_read_b128 v[136:139], v148
	ds_read_b128 v[140:143], v148 offset:1024
	ds_read_b128 v[144:147], v148 offset:2048
	ds_read_b128 v[148:151], v148 offset:3072
	ds_read_b128 v[152:155], v164
	ds_read_b128 v[156:159], v164 offset:1024
	ds_read_b128 v[160:163], v164 offset:2048
	ds_read_b128 v[164:167], v164 offset:3072
	s_add_u32 s16, s16, 0x80000
	s_addc_u32 s17, s17, 0
	s_mov_b32 m0, s47
	v_lshl_add_u64 v[202:203], s[16:17], 0, v[0:1]
	ds_read_b128 v[168:171], v242 offset:32768
	ds_read_b128 v[186:189], v242 offset:33792
	ds_read_b128 v[190:193], v242 offset:34816
	ds_read_b128 v[204:207], v242 offset:35840
	ds_read_b128 v[208:211], v242 offset:36864
	ds_read_b128 v[212:215], v242 offset:37888
	ds_read_b128 v[244:247], v242 offset:38912
	ds_read_b128 v[248:251], v242 offset:39936
	global_load_lds_dwordx4 v[202:203], off
	v_lshl_add_u64 v[202:203], s[16:17], 0, v[174:175]
	s_mov_b32 m0, s51
	s_nop 0
	global_load_lds_dwordx4 v[202:203], off
	s_waitcnt vmcnt(8)
	s_waitcnt lgkmcnt(0)
	s_setprio 1
	s_barrier
	v_mfma_f32_16x16x32_bf16 v[8:11], v[136:139], v[168:171], v[8:11]
	v_mfma_f32_16x16x32_bf16 v[128:131], v[144:147], v[168:171], v[128:131]
	v_mfma_f32_16x16x32_bf16 v[124:127], v[136:139], v[190:193], v[124:127]
	v_mfma_f32_16x16x32_bf16 v[120:123], v[144:147], v[190:193], v[120:123]
	v_mfma_f32_16x16x32_bf16 v[116:119], v[136:139], v[208:211], v[116:119]
	v_mfma_f32_16x16x32_bf16 v[112:115], v[144:147], v[208:211], v[112:115]
	v_mfma_f32_16x16x32_bf16 v[108:111], v[136:139], v[244:247], v[108:111]
	v_mfma_f32_16x16x32_bf16 v[104:107], v[144:147], v[244:247], v[104:107]
	v_mfma_f32_16x16x32_bf16 v[8:11], v[140:143], v[186:189], v[8:11]
	v_mfma_f32_16x16x32_bf16 v[128:131], v[148:151], v[186:189], v[128:131]
	v_mfma_f32_16x16x32_bf16 v[124:127], v[140:143], v[204:207], v[124:127]
	v_mfma_f32_16x16x32_bf16 v[120:123], v[148:151], v[204:207], v[120:123]
	v_mfma_f32_16x16x32_bf16 v[116:119], v[140:143], v[212:215], v[116:119]
	v_mfma_f32_16x16x32_bf16 v[112:115], v[148:151], v[212:215], v[112:115]
	v_mfma_f32_16x16x32_bf16 v[108:111], v[140:143], v[248:251], v[108:111]
	v_mfma_f32_16x16x32_bf16 v[104:107], v[148:151], v[248:251], v[104:107]
	v_mfma_f32_16x16x32_bf16 v[100:103], v[152:155], v[168:171], v[100:103]
	v_mfma_f32_16x16x32_bf16 v[96:99], v[160:163], v[168:171], v[96:99]
	v_mfma_f32_16x16x32_bf16 v[92:95], v[152:155], v[190:193], v[92:95]
	v_mfma_f32_16x16x32_bf16 v[88:91], v[160:163], v[190:193], v[88:91]
	v_mfma_f32_16x16x32_bf16 v[84:87], v[152:155], v[208:211], v[84:87]
	v_mfma_f32_16x16x32_bf16 v[80:83], v[160:163], v[208:211], v[80:83]
	v_mfma_f32_16x16x32_bf16 v[76:79], v[152:155], v[244:247], v[76:79]
	v_mfma_f32_16x16x32_bf16 v[72:75], v[160:163], v[244:247], v[72:75]
	v_mfma_f32_16x16x32_bf16 v[100:103], v[156:159], v[186:189], v[100:103]
	v_mfma_f32_16x16x32_bf16 v[96:99], v[164:167], v[186:189], v[96:99]
	v_mfma_f32_16x16x32_bf16 v[92:95], v[156:159], v[204:207], v[92:95]
	v_mfma_f32_16x16x32_bf16 v[88:91], v[164:167], v[204:207], v[88:91]
	v_mfma_f32_16x16x32_bf16 v[84:87], v[156:159], v[212:215], v[84:87]
	v_mfma_f32_16x16x32_bf16 v[80:83], v[164:167], v[212:215], v[80:83]
	v_mfma_f32_16x16x32_bf16 v[76:79], v[156:159], v[248:251], v[76:79]
	v_mfma_f32_16x16x32_bf16 v[72:75], v[164:167], v[248:251], v[72:75]
	s_setprio 0
	s_barrier
	s_add_i32 s16, s43, s38
	v_lshl_add_u64 v[194:195], v[194:195], 0, s[70:71]
	s_mov_b32 m0, s16
	ds_read_b128 v[168:171], v242 offset:49152
	ds_read_b128 v[186:189], v242 offset:50176
	ds_read_b128 v[190:193], v242 offset:51200
	ds_read_b128 v[204:207], v242 offset:52224
	ds_read_b128 v[208:211], v242 offset:53248
	ds_read_b128 v[212:215], v242 offset:54272
	ds_read_b128 v[244:247], v242 offset:55296
	ds_read_b128 v[248:251], v242 offset:56320
	global_load_lds_dwordx4 v[194:195], off
	s_add_i32 m0, s16, 0x2000
	s_add_u32 s12, s12, 0x80080
	v_lshl_add_u64 v[194:195], v[196:197], 0, s[70:71]
	s_addc_u32 s13, s13, 0
	s_add_i32 s16, s66, s38
	global_load_lds_dwordx4 v[194:195], off
	v_lshl_add_u64 v[194:195], s[12:13], 0, v[172:173]
	s_mov_b32 m0, s16
	s_nop 0
	global_load_lds_dwordx4 v[194:195], off
	v_lshl_add_u64 v[194:195], s[12:13], 0, v[176:177]
	s_add_i32 m0, s16, 0x2000
	s_nop 0
	global_load_lds_dwordx4 v[194:195], off
	v_lshl_add_u64 v[194:195], v[198:199], 0, s[70:71]
	s_mov_b32 m0, s52
	s_nop 0
	global_load_lds_dwordx4 v[194:195], off
	v_lshl_add_u64 v[194:195], v[200:201], 0, s[70:71]
	s_mov_b32 m0, s54
	s_nop 0
	global_load_lds_dwordx4 v[194:195], off
	s_waitcnt vmcnt(8)
	s_waitcnt lgkmcnt(0)
	s_setprio 1
	s_barrier
	v_mfma_f32_16x16x32_bf16 v[68:71], v[136:139], v[168:171], v[68:71]
	v_mfma_f32_16x16x32_bf16 v[64:67], v[144:147], v[168:171], v[64:67]
	v_mfma_f32_16x16x32_bf16 v[60:63], v[136:139], v[190:193], v[60:63]
	v_mfma_f32_16x16x32_bf16 v[56:59], v[144:147], v[190:193], v[56:59]
	v_mfma_f32_16x16x32_bf16 v[52:55], v[136:139], v[208:211], v[52:55]
	v_mfma_f32_16x16x32_bf16 v[48:51], v[144:147], v[208:211], v[48:51]
	v_mfma_f32_16x16x32_bf16 v[44:47], v[136:139], v[244:247], v[44:47]
	v_mfma_f32_16x16x32_bf16 v[40:43], v[144:147], v[244:247], v[40:43]
	v_mfma_f32_16x16x32_bf16 v[68:71], v[140:143], v[186:189], v[68:71]
	v_mfma_f32_16x16x32_bf16 v[64:67], v[148:151], v[186:189], v[64:67]
	v_mfma_f32_16x16x32_bf16 v[60:63], v[140:143], v[204:207], v[60:63]
	v_mfma_f32_16x16x32_bf16 v[56:59], v[148:151], v[204:207], v[56:59]
	v_mfma_f32_16x16x32_bf16 v[52:55], v[140:143], v[212:215], v[52:55]
	v_mfma_f32_16x16x32_bf16 v[48:51], v[148:151], v[212:215], v[48:51]
	v_mfma_f32_16x16x32_bf16 v[44:47], v[140:143], v[248:251], v[44:47]
	v_mfma_f32_16x16x32_bf16 v[40:43], v[148:151], v[248:251], v[40:43]
	v_mfma_f32_16x16x32_bf16 v[36:39], v[152:155], v[168:171], v[36:39]
	v_mfma_f32_16x16x32_bf16 v[32:35], v[160:163], v[168:171], v[32:35]
	v_mfma_f32_16x16x32_bf16 v[28:31], v[152:155], v[190:193], v[28:31]
	v_mfma_f32_16x16x32_bf16 v[24:27], v[160:163], v[190:193], v[24:27]
	v_mfma_f32_16x16x32_bf16 v[20:23], v[152:155], v[208:211], v[20:23]
	v_mfma_f32_16x16x32_bf16 v[16:19], v[160:163], v[208:211], v[16:19]
	v_mfma_f32_16x16x32_bf16 v[12:15], v[152:155], v[244:247], v[12:15]
	v_mfma_f32_16x16x32_bf16 v[4:7], v[160:163], v[244:247], v[4:7]
	v_mfma_f32_16x16x32_bf16 v[36:39], v[156:159], v[186:189], v[36:39]
	v_mfma_f32_16x16x32_bf16 v[32:35], v[164:167], v[186:189], v[32:35]
	v_mfma_f32_16x16x32_bf16 v[28:31], v[156:159], v[204:207], v[28:31]
	v_mfma_f32_16x16x32_bf16 v[24:27], v[164:167], v[204:207], v[24:27]
	v_mfma_f32_16x16x32_bf16 v[20:23], v[156:159], v[212:215], v[20:23]
	v_mfma_f32_16x16x32_bf16 v[16:19], v[164:167], v[212:215], v[16:19]
	v_mfma_f32_16x16x32_bf16 v[12:15], v[156:159], v[248:251], v[12:15]
	v_mfma_f32_16x16x32_bf16 v[4:7], v[164:167], v[248:251], v[4:7]
	s_setprio 0
	s_barrier
	s_add_i32 s42, s42, 2
	s_add_u32 s8, s8, 0x100
	s_addc_u32 s9, s9, 0
	s_cmp_gt_u32 s42, 29
	s_cbranch_scc0 .LBB0_319
	s_and_b64 vcc, exec, s[22:23]
	s_cbranch_vccz .LBB0_322
	s_barrier

.LBB0_803:
	s_add_u32 s12, s28, s8
	s_addc_u32 s13, s29, s9
	s_add_u32 s12, s12, 0x100
	s_addc_u32 s13, s13, 0
	s_add_u32 s81, s84, s8
	s_addc_u32 s83, s85, s9
	s_add_i32 s95, 0, 0x10000
	s_cmpk_eq_i32 s8, 0xf00
	s_cselect_b32 s37, s27, s13
	s_cselect_b32 s36, s42, s12
	s_cselect_b32 s13, s25, s83
	s_cselect_b32 s12, s43, s81
	s_add_i32 s81, 0, 0x14000
	v_add_u32_e32 v148, s95, v207
	v_add_u32_e32 v176, s81, v207
	ds_read_b128 v[136:139], v148
	ds_read_b128 v[140:143], v148 offset:1024
	ds_read_b128 v[144:147], v148 offset:2048
	ds_read_b128 v[148:151], v148 offset:3072
	ds_read_b128 v[152:155], v176
	ds_read_b128 v[156:159], v176 offset:1024
	ds_read_b128 v[160:163], v176 offset:2048
	s_waitcnt lgkmcnt(0)
	ds_read_b128 v[176:179], v176 offset:3072
	v_lshl_add_u64 v[196:197], v[132:133], 0, s[8:9]
	s_add_i32 m0, s75, 0xc000
	ds_read_b128 v[180:183], v209
	ds_read_b128 v[184:187], v209 offset:1024
	ds_read_b128 v[188:191], v209 offset:2048
	ds_read_b128 v[192:195], v209 offset:3072
	ds_read_b128 v[212:215], v209 offset:4096
	ds_read_b128 v[226:229], v209 offset:5120
	ds_read_b128 v[230:233], v209 offset:6144
	ds_read_b128 v[234:237], v209 offset:7168
	global_load_lds_dwordx4 v[196:197], off
	v_lshl_add_u64 v[196:197], v[134:135], 0, s[8:9]
	s_add_i32 m0, s75, 0xe000
	s_nop 0
	global_load_lds_dwordx4 v[196:197], off
	s_waitcnt vmcnt(8)
	s_waitcnt lgkmcnt(0)
	s_setprio 1
	s_barrier
	v_mfma_f32_16x16x32_bf16 v[8:11], v[136:139], v[180:183], v[8:11]
	v_mfma_f32_16x16x32_bf16 v[128:131], v[144:147], v[180:183], v[128:131]
	v_mfma_f32_16x16x32_bf16 v[124:127], v[136:139], v[188:191], v[124:127]
	v_mfma_f32_16x16x32_bf16 v[120:123], v[144:147], v[188:191], v[120:123]
	v_mfma_f32_16x16x32_bf16 v[116:119], v[136:139], v[212:215], v[116:119]
	v_mfma_f32_16x16x32_bf16 v[112:115], v[144:147], v[212:215], v[112:115]
	v_mfma_f32_16x16x32_bf16 v[108:111], v[136:139], v[230:233], v[108:111]
	v_mfma_f32_16x16x32_bf16 v[104:107], v[144:147], v[230:233], v[104:107]
	v_mfma_f32_16x16x32_bf16 v[8:11], v[140:143], v[184:187], v[8:11]
	v_mfma_f32_16x16x32_bf16 v[128:131], v[148:151], v[184:187], v[128:131]
	v_mfma_f32_16x16x32_bf16 v[124:127], v[140:143], v[192:195], v[124:127]
	v_mfma_f32_16x16x32_bf16 v[120:123], v[148:151], v[192:195], v[120:123]
	v_mfma_f32_16x16x32_bf16 v[116:119], v[140:143], v[226:229], v[116:119]
	v_mfma_f32_16x16x32_bf16 v[112:115], v[148:151], v[226:229], v[112:115]
	v_mfma_f32_16x16x32_bf16 v[108:111], v[140:143], v[234:237], v[108:111]
	v_mfma_f32_16x16x32_bf16 v[104:107], v[148:151], v[234:237], v[104:107]
	v_mfma_f32_16x16x32_bf16 v[100:103], v[152:155], v[180:183], v[100:103]
	v_mfma_f32_16x16x32_bf16 v[96:99], v[160:163], v[180:183], v[96:99]
	v_mfma_f32_16x16x32_bf16 v[92:95], v[152:155], v[188:191], v[92:95]
	v_mfma_f32_16x16x32_bf16 v[88:91], v[160:163], v[188:191], v[88:91]
	v_mfma_f32_16x16x32_bf16 v[84:87], v[152:155], v[212:215], v[84:87]
	v_mfma_f32_16x16x32_bf16 v[80:83], v[160:163], v[212:215], v[80:83]
	v_mfma_f32_16x16x32_bf16 v[76:79], v[152:155], v[230:233], v[76:79]
	v_mfma_f32_16x16x32_bf16 v[72:75], v[160:163], v[230:233], v[72:75]
	v_mfma_f32_16x16x32_bf16 v[100:103], v[156:159], v[184:187], v[100:103]
	v_mfma_f32_16x16x32_bf16 v[96:99], v[176:179], v[184:187], v[96:99]
	v_mfma_f32_16x16x32_bf16 v[92:95], v[156:159], v[192:195], v[92:95]
	v_mfma_f32_16x16x32_bf16 v[88:91], v[176:179], v[192:195], v[88:91]
	v_mfma_f32_16x16x32_bf16 v[84:87], v[156:159], v[226:229], v[84:87]
	v_mfma_f32_16x16x32_bf16 v[80:83], v[176:179], v[226:229], v[80:83]
	v_mfma_f32_16x16x32_bf16 v[76:79], v[156:159], v[234:237], v[76:79]
	v_mfma_f32_16x16x32_bf16 v[72:75], v[176:179], v[234:237], v[72:75]
	s_setprio 0
	s_barrier
	s_add_i32 s83, s95, s74
	v_lshl_add_u64 v[196:197], s[12:13], 0, v[164:165]
	s_mov_b32 m0, s83
	ds_read_b128 v[180:183], v209 offset:16384
	ds_read_b128 v[184:187], v209 offset:17408
	ds_read_b128 v[188:191], v209 offset:18432
	ds_read_b128 v[192:195], v209 offset:19456
	ds_read_b128 v[212:215], v209 offset:20480
	ds_read_b128 v[226:229], v209 offset:21504
	ds_read_b128 v[230:233], v209 offset:22528
	ds_read_b128 v[234:237], v209 offset:23552
	global_load_lds_dwordx4 v[196:197], off
	s_add_i32 m0, s83, 0x2000
	s_add_u32 vcc_lo, s12, 0x80000
	v_lshl_add_u64 v[198:199], s[12:13], 0, v[168:169]
	s_addc_u32 vcc_hi, s13, 0
	s_add_i32 s81, s81, s74
	global_load_lds_dwordx4 v[198:199], off
	v_lshl_add_u64 v[200:201], vcc, 0, v[164:165]
	s_mov_b32 m0, s81
	v_lshl_add_u64 v[202:203], s[36:37], 0, v[166:167]
	global_load_lds_dwordx4 v[200:201], off
	v_lshl_add_u64 v[200:201], vcc, 0, v[168:169]
	s_add_i32 m0, s81, 0x2000
	s_nop 0
	global_load_lds_dwordx4 v[200:201], off
	v_lshl_add_u64 v[200:201], s[36:37], 0, v[0:1]
	s_mov_b32 m0, s75
	s_nop 0
	global_load_lds_dwordx4 v[200:201], off
	s_mov_b32 m0, s15
	s_nop 0
	global_load_lds_dwordx4 v[202:203], off
	s_waitcnt vmcnt(8)
	s_waitcnt lgkmcnt(0)
	s_setprio 1
	s_barrier
	v_mfma_f32_16x16x32_bf16 v[68:71], v[136:139], v[180:183], v[68:71]
	v_mfma_f32_16x16x32_bf16 v[64:67], v[144:147], v[180:183], v[64:67]
	v_mfma_f32_16x16x32_bf16 v[60:63], v[136:139], v[188:191], v[60:63]
	v_mfma_f32_16x16x32_bf16 v[56:59], v[144:147], v[188:191], v[56:59]
	v_mfma_f32_16x16x32_bf16 v[52:55], v[136:139], v[212:215], v[52:55]
	v_mfma_f32_16x16x32_bf16 v[48:51], v[144:147], v[212:215], v[48:51]
	v_mfma_f32_16x16x32_bf16 v[44:47], v[136:139], v[230:233], v[44:47]
	v_mfma_f32_16x16x32_bf16 v[40:43], v[144:147], v[230:233], v[40:43]
	v_mfma_f32_16x16x32_bf16 v[68:71], v[140:143], v[184:187], v[68:71]
	v_mfma_f32_16x16x32_bf16 v[64:67], v[148:151], v[184:187], v[64:67]
	v_mfma_f32_16x16x32_bf16 v[60:63], v[140:143], v[192:195], v[60:63]
	v_mfma_f32_16x16x32_bf16 v[56:59], v[148:151], v[192:195], v[56:59]
	v_mfma_f32_16x16x32_bf16 v[52:55], v[140:143], v[226:229], v[52:55]
	v_mfma_f32_16x16x32_bf16 v[48:51], v[148:151], v[226:229], v[48:51]
	v_mfma_f32_16x16x32_bf16 v[44:47], v[140:143], v[234:237], v[44:47]
	v_mfma_f32_16x16x32_bf16 v[40:43], v[148:151], v[234:237], v[40:43]
	v_mfma_f32_16x16x32_bf16 v[36:39], v[152:155], v[180:183], v[36:39]
	v_mfma_f32_16x16x32_bf16 v[32:35], v[160:163], v[180:183], v[32:35]
	v_mfma_f32_16x16x32_bf16 v[28:31], v[152:155], v[188:191], v[28:31]
	v_mfma_f32_16x16x32_bf16 v[24:27], v[160:163], v[188:191], v[24:27]
	v_mfma_f32_16x16x32_bf16 v[20:23], v[152:155], v[212:215], v[20:23]
	v_mfma_f32_16x16x32_bf16 v[16:19], v[160:163], v[212:215], v[16:19]
	v_mfma_f32_16x16x32_bf16 v[12:15], v[152:155], v[230:233], v[12:15]
	v_mfma_f32_16x16x32_bf16 v[4:7], v[160:163], v[230:233], v[4:7]
	v_mfma_f32_16x16x32_bf16 v[36:39], v[156:159], v[184:187], v[36:39]
	v_mfma_f32_16x16x32_bf16 v[32:35], v[176:179], v[184:187], v[32:35]
	v_mfma_f32_16x16x32_bf16 v[28:31], v[156:159], v[192:195], v[28:31]
	v_mfma_f32_16x16x32_bf16 v[24:27], v[176:179], v[192:195], v[24:27]
	v_mfma_f32_16x16x32_bf16 v[20:23], v[156:159], v[226:229], v[20:23]
	v_mfma_f32_16x16x32_bf16 v[16:19], v[176:179], v[226:229], v[16:19]
	v_mfma_f32_16x16x32_bf16 v[12:15], v[156:159], v[234:237], v[12:15]
	v_mfma_f32_16x16x32_bf16 v[4:7], v[176:179], v[234:237], v[4:7]
	s_setprio 0
	s_barrier
	s_add_i32 s81, 0, 0x18000
	s_add_i32 s83, 0, 0x1c000
	v_add_u32_e32 v148, s81, v207
	v_add_u32_e32 v176, s83, v207
	ds_read_b128 v[136:139], v148
	ds_read_b128 v[140:143], v148 offset:1024
	ds_read_b128 v[144:147], v148 offset:2048
	ds_read_b128 v[148:151], v148 offset:3072
	ds_read_b128 v[152:155], v176
	ds_read_b128 v[156:159], v176 offset:1024
	ds_read_b128 v[160:163], v176 offset:2048
	ds_read_b128 v[176:179], v176 offset:3072
	s_add_u32 s36, s36, 0x80000
	s_addc_u32 s37, s37, 0
	s_mov_b32 m0, s38
	v_lshl_add_u64 v[216:217], s[36:37], 0, v[0:1]
	ds_read_b128 v[180:183], v209 offset:32768
	ds_read_b128 v[184:187], v209 offset:33792
	ds_read_b128 v[188:191], v209 offset:34816
	ds_read_b128 v[192:195], v209 offset:35840
	ds_read_b128 v[212:215], v209 offset:36864
	ds_read_b128 v[226:229], v209 offset:37888
	ds_read_b128 v[230:233], v209 offset:38912
	ds_read_b128 v[234:237], v209 offset:39936
	global_load_lds_dwordx4 v[216:217], off
	v_lshl_add_u64 v[216:217], s[36:37], 0, v[166:167]
	s_mov_b32 m0, s39
	s_nop 0
	global_load_lds_dwordx4 v[216:217], off
	s_waitcnt vmcnt(8)
	s_waitcnt lgkmcnt(0)
	s_setprio 1
	s_barrier
	v_mfma_f32_16x16x32_bf16 v[8:11], v[136:139], v[180:183], v[8:11]
	v_mfma_f32_16x16x32_bf16 v[128:131], v[144:147], v[180:183], v[128:131]
	v_mfma_f32_16x16x32_bf16 v[124:127], v[136:139], v[188:191], v[124:127]
	v_mfma_f32_16x16x32_bf16 v[120:123], v[144:147], v[188:191], v[120:123]
	v_mfma_f32_16x16x32_bf16 v[116:119], v[136:139], v[212:215], v[116:119]
	v_mfma_f32_16x16x32_bf16 v[112:115], v[144:147], v[212:215], v[112:115]
	v_mfma_f32_16x16x32_bf16 v[108:111], v[136:139], v[230:233], v[108:111]
	v_mfma_f32_16x16x32_bf16 v[104:107], v[144:147], v[230:233], v[104:107]
	v_mfma_f32_16x16x32_bf16 v[8:11], v[140:143], v[184:187], v[8:11]
	v_mfma_f32_16x16x32_bf16 v[128:131], v[148:151], v[184:187], v[128:131]
	v_mfma_f32_16x16x32_bf16 v[124:127], v[140:143], v[192:195], v[124:127]
	v_mfma_f32_16x16x32_bf16 v[120:123], v[148:151], v[192:195], v[120:123]
	v_mfma_f32_16x16x32_bf16 v[116:119], v[140:143], v[226:229], v[116:119]
	v_mfma_f32_16x16x32_bf16 v[112:115], v[148:151], v[226:229], v[112:115]
	v_mfma_f32_16x16x32_bf16 v[108:111], v[140:143], v[234:237], v[108:111]
	v_mfma_f32_16x16x32_bf16 v[104:107], v[148:151], v[234:237], v[104:107]
	v_mfma_f32_16x16x32_bf16 v[100:103], v[152:155], v[180:183], v[100:103]
	v_mfma_f32_16x16x32_bf16 v[96:99], v[160:163], v[180:183], v[96:99]
	v_mfma_f32_16x16x32_bf16 v[92:95], v[152:155], v[188:191], v[92:95]
	v_mfma_f32_16x16x32_bf16 v[88:91], v[160:163], v[188:191], v[88:91]
	v_mfma_f32_16x16x32_bf16 v[84:87], v[152:155], v[212:215], v[84:87]
	v_mfma_f32_16x16x32_bf16 v[80:83], v[160:163], v[212:215], v[80:83]
	v_mfma_f32_16x16x32_bf16 v[76:79], v[152:155], v[230:233], v[76:79]
	v_mfma_f32_16x16x32_bf16 v[72:75], v[160:163], v[230:233], v[72:75]
	v_mfma_f32_16x16x32_bf16 v[100:103], v[156:159], v[184:187], v[100:103]
	v_mfma_f32_16x16x32_bf16 v[96:99], v[176:179], v[184:187], v[96:99]
	v_mfma_f32_16x16x32_bf16 v[92:95], v[156:159], v[192:195], v[92:95]
	v_mfma_f32_16x16x32_bf16 v[88:91], v[176:179], v[192:195], v[88:91]
	v_mfma_f32_16x16x32_bf16 v[84:87], v[156:159], v[226:229], v[84:87]
	v_mfma_f32_16x16x32_bf16 v[80:83], v[176:179], v[226:229], v[80:83]
	v_mfma_f32_16x16x32_bf16 v[76:79], v[156:159], v[234:237], v[76:79]
	v_mfma_f32_16x16x32_bf16 v[72:75], v[176:179], v[234:237], v[72:75]
	s_setprio 0
	s_barrier
	s_add_i32 s36, s81, s74
	v_lshl_add_u64 v[196:197], v[196:197], 0, s[70:71]
	s_mov_b32 m0, s36
	ds_read_b128 v[180:183], v209 offset:49152
	ds_read_b128 v[184:187], v209 offset:50176
	ds_read_b128 v[188:191], v209 offset:51200
	ds_read_b128 v[192:195], v209 offset:52224
	ds_read_b128 v[212:215], v209 offset:53248
	ds_read_b128 v[226:229], v209 offset:54272
	ds_read_b128 v[230:233], v209 offset:55296
	ds_read_b128 v[234:237], v209 offset:56320
	global_load_lds_dwordx4 v[196:197], off
	s_add_i32 m0, s36, 0x2000
	s_add_u32 s12, s12, 0x80080
	v_lshl_add_u64 v[196:197], v[198:199], 0, s[70:71]
	s_addc_u32 s13, s13, 0
	s_add_i32 s36, s83, s74
	global_load_lds_dwordx4 v[196:197], off
	v_lshl_add_u64 v[196:197], s[12:13], 0, v[164:165]
	s_mov_b32 m0, s36
	s_nop 0
	global_load_lds_dwordx4 v[196:197], off
	v_lshl_add_u64 v[196:197], s[12:13], 0, v[168:169]
	s_add_i32 m0, s36, 0x2000
	s_nop 0
	global_load_lds_dwordx4 v[196:197], off
	v_lshl_add_u64 v[196:197], v[200:201], 0, s[70:71]
	s_mov_b32 m0, s51
	s_nop 0
	global_load_lds_dwordx4 v[196:197], off
	v_lshl_add_u64 v[196:197], v[202:203], 0, s[70:71]
	s_mov_b32 m0, s92
	s_nop 0
	global_load_lds_dwordx4 v[196:197], off
	s_waitcnt vmcnt(8)
	s_waitcnt lgkmcnt(0)
	s_setprio 1
	s_barrier
	v_mfma_f32_16x16x32_bf16 v[68:71], v[136:139], v[180:183], v[68:71]
	v_mfma_f32_16x16x32_bf16 v[64:67], v[144:147], v[180:183], v[64:67]
	v_mfma_f32_16x16x32_bf16 v[60:63], v[136:139], v[188:191], v[60:63]
	v_mfma_f32_16x16x32_bf16 v[56:59], v[144:147], v[188:191], v[56:59]
	v_mfma_f32_16x16x32_bf16 v[52:55], v[136:139], v[212:215], v[52:55]
	v_mfma_f32_16x16x32_bf16 v[48:51], v[144:147], v[212:215], v[48:51]
	v_mfma_f32_16x16x32_bf16 v[44:47], v[136:139], v[230:233], v[44:47]
	v_mfma_f32_16x16x32_bf16 v[40:43], v[144:147], v[230:233], v[40:43]
	v_mfma_f32_16x16x32_bf16 v[68:71], v[140:143], v[184:187], v[68:71]
	v_mfma_f32_16x16x32_bf16 v[64:67], v[148:151], v[184:187], v[64:67]
	v_mfma_f32_16x16x32_bf16 v[60:63], v[140:143], v[192:195], v[60:63]
	v_mfma_f32_16x16x32_bf16 v[56:59], v[148:151], v[192:195], v[56:59]
	v_mfma_f32_16x16x32_bf16 v[52:55], v[140:143], v[226:229], v[52:55]
	v_mfma_f32_16x16x32_bf16 v[48:51], v[148:151], v[226:229], v[48:51]
	v_mfma_f32_16x16x32_bf16 v[44:47], v[140:143], v[234:237], v[44:47]
	v_mfma_f32_16x16x32_bf16 v[40:43], v[148:151], v[234:237], v[40:43]
	v_mfma_f32_16x16x32_bf16 v[36:39], v[152:155], v[180:183], v[36:39]
	v_mfma_f32_16x16x32_bf16 v[32:35], v[160:163], v[180:183], v[32:35]
	v_mfma_f32_16x16x32_bf16 v[28:31], v[152:155], v[188:191], v[28:31]
	v_mfma_f32_16x16x32_bf16 v[24:27], v[160:163], v[188:191], v[24:27]
	v_mfma_f32_16x16x32_bf16 v[20:23], v[152:155], v[212:215], v[20:23]
	v_mfma_f32_16x16x32_bf16 v[16:19], v[160:163], v[212:215], v[16:19]
	v_mfma_f32_16x16x32_bf16 v[12:15], v[152:155], v[230:233], v[12:15]
	v_mfma_f32_16x16x32_bf16 v[4:7], v[160:163], v[230:233], v[4:7]
	v_mfma_f32_16x16x32_bf16 v[36:39], v[156:159], v[184:187], v[36:39]
	v_mfma_f32_16x16x32_bf16 v[32:35], v[176:179], v[184:187], v[32:35]
	v_mfma_f32_16x16x32_bf16 v[28:31], v[156:159], v[192:195], v[28:31]
	v_mfma_f32_16x16x32_bf16 v[24:27], v[176:179], v[192:195], v[24:27]
	v_mfma_f32_16x16x32_bf16 v[20:23], v[156:159], v[226:229], v[20:23]
	v_mfma_f32_16x16x32_bf16 v[16:19], v[176:179], v[226:229], v[16:19]
	v_mfma_f32_16x16x32_bf16 v[12:15], v[156:159], v[234:237], v[12:15]
	v_mfma_f32_16x16x32_bf16 v[4:7], v[176:179], v[234:237], v[4:7]
	s_setprio 0
	s_barrier
	s_add_i32 s52, s52, 2
	s_add_u32 s8, s8, 0x100
	s_addc_u32 s9, s9, 0
	s_cmp_gt_u32 s52, 29
	s_cbranch_scc0 .LBB0_803
	s_and_b64 vcc, exec, s[22:23]
	s_cbranch_vccz .LBB0_806
	s_barrier

.LBB0_975:
	s_add_u32 s34, s30, 0xfff80080
	s_addc_u32 s35, s31, -1
	s_add_i32 s81, 0, 0x10000
	s_cmp_eq_u32 s75, 28
	s_cselect_b32 s37, s25, s35
	s_cselect_b32 s36, s66, s34
	s_cselect_b32 s35, s23, s74
	s_cselect_b32 s34, s67, s69
	s_add_i32 s83, 0, 0x14000
	v_add_u32_e32 v144, s81, v182
	v_add_u32_e32 v170, s83, v182
	ds_read_b128 v[132:135], v144
	ds_read_b128 v[136:139], v144 offset:1024
	ds_read_b128 v[140:143], v144 offset:2048
	ds_read_b128 v[144:147], v144 offset:3072
	ds_read_b128 v[148:151], v170
	ds_read_b128 v[152:155], v170 offset:1024
	ds_read_b128 v[156:159], v170 offset:2048
	ds_read_b128 v[170:173], v170 offset:3072
	v_lshl_add_u64 v[212:213], s[30:31], 0, v[166:167]
	s_add_i32 m0, s15, 0xc000
	ds_read_b128 v[174:177], v186
	ds_read_b128 v[178:181], v186 offset:1024
	ds_read_b128 v[188:191], v186 offset:2048
	ds_read_b128 v[192:195], v186 offset:3072
	ds_read_b128 v[196:199], v186 offset:4096
	ds_read_b128 v[200:203], v186 offset:5120
	ds_read_b128 v[204:207], v186 offset:6144
	ds_read_b128 v[208:211], v186 offset:7168
	global_load_lds_dwordx4 v[212:213], off
	v_lshl_add_u64 v[212:213], s[30:31], 0, v[168:169]
	s_add_i32 m0, s15, 0xe000
	s_nop 0
	global_load_lds_dwordx4 v[212:213], off
	s_waitcnt vmcnt(8)
	s_waitcnt lgkmcnt(0)
	s_setprio 1
	s_barrier
	v_mfma_f32_16x16x32_bf16 v[128:131], v[132:135], v[174:177], v[128:131]
	v_mfma_f32_16x16x32_bf16 v[124:127], v[140:143], v[174:177], v[124:127]
	v_mfma_f32_16x16x32_bf16 v[112:115], v[132:135], v[188:191], v[112:115]
	v_mfma_f32_16x16x32_bf16 v[108:111], v[140:143], v[188:191], v[108:111]
	v_mfma_f32_16x16x32_bf16 v[96:99], v[132:135], v[196:199], v[96:99]
	v_mfma_f32_16x16x32_bf16 v[92:95], v[140:143], v[196:199], v[92:95]
	v_mfma_f32_16x16x32_bf16 v[80:83], v[132:135], v[204:207], v[80:83]
	v_mfma_f32_16x16x32_bf16 v[76:79], v[140:143], v[204:207], v[76:79]
	v_mfma_f32_16x16x32_bf16 v[128:131], v[136:139], v[178:181], v[128:131]
	v_mfma_f32_16x16x32_bf16 v[124:127], v[144:147], v[178:181], v[124:127]
	v_mfma_f32_16x16x32_bf16 v[112:115], v[136:139], v[192:195], v[112:115]
	v_mfma_f32_16x16x32_bf16 v[108:111], v[144:147], v[192:195], v[108:111]
	v_mfma_f32_16x16x32_bf16 v[96:99], v[136:139], v[200:203], v[96:99]
	v_mfma_f32_16x16x32_bf16 v[92:95], v[144:147], v[200:203], v[92:95]
	v_mfma_f32_16x16x32_bf16 v[80:83], v[136:139], v[208:211], v[80:83]
	v_mfma_f32_16x16x32_bf16 v[76:79], v[144:147], v[208:211], v[76:79]
	v_mfma_f32_16x16x32_bf16 v[120:123], v[148:151], v[174:177], v[120:123]
	v_mfma_f32_16x16x32_bf16 v[116:119], v[156:159], v[174:177], v[116:119]
	v_mfma_f32_16x16x32_bf16 v[104:107], v[148:151], v[188:191], v[104:107]
	v_mfma_f32_16x16x32_bf16 v[100:103], v[156:159], v[188:191], v[100:103]
	v_mfma_f32_16x16x32_bf16 v[88:91], v[148:151], v[196:199], v[88:91]
	v_mfma_f32_16x16x32_bf16 v[84:87], v[156:159], v[196:199], v[84:87]
	v_mfma_f32_16x16x32_bf16 v[72:75], v[148:151], v[204:207], v[72:75]
	v_mfma_f32_16x16x32_bf16 v[68:71], v[156:159], v[204:207], v[68:71]
	v_mfma_f32_16x16x32_bf16 v[120:123], v[152:155], v[178:181], v[120:123]
	v_mfma_f32_16x16x32_bf16 v[116:119], v[170:173], v[178:181], v[116:119]
	v_mfma_f32_16x16x32_bf16 v[104:107], v[152:155], v[192:195], v[104:107]
	v_mfma_f32_16x16x32_bf16 v[100:103], v[170:173], v[192:195], v[100:103]
	v_mfma_f32_16x16x32_bf16 v[88:91], v[152:155], v[200:203], v[88:91]
	v_mfma_f32_16x16x32_bf16 v[84:87], v[170:173], v[200:203], v[84:87]
	v_mfma_f32_16x16x32_bf16 v[72:75], v[152:155], v[208:211], v[72:75]
	v_mfma_f32_16x16x32_bf16 v[68:71], v[170:173], v[208:211], v[68:71]
	s_setprio 0
	s_barrier
	s_add_i32 s81, s81, s0
	v_lshl_add_u64 v[212:213], s[34:35], 0, v[162:163]
	s_mov_b32 m0, s81
	ds_read_b128 v[174:177], v186 offset:16384
	ds_read_b128 v[178:181], v186 offset:17408
	ds_read_b128 v[188:191], v186 offset:18432
	ds_read_b128 v[192:195], v186 offset:19456
	ds_read_b128 v[196:199], v186 offset:20480
	ds_read_b128 v[200:203], v186 offset:21504
	ds_read_b128 v[204:207], v186 offset:22528
	ds_read_b128 v[208:211], v186 offset:23552
	global_load_lds_dwordx4 v[212:213], off
	s_add_i32 m0, s81, 0x2000
	s_add_u32 s84, s34, 0x80000
	v_lshl_add_u64 v[214:215], s[34:35], 0, v[0:1]
	s_addc_u32 s85, s35, 0
	s_add_i32 s81, s83, s0
	global_load_lds_dwordx4 v[214:215], off
	v_lshl_add_u64 v[216:217], s[84:85], 0, v[162:163]
	s_mov_b32 m0, s81
	v_lshl_add_u64 v[226:227], s[36:37], 0, v[160:161]
	global_load_lds_dwordx4 v[216:217], off
	v_lshl_add_u64 v[216:217], s[84:85], 0, v[0:1]
	s_add_i32 m0, s81, 0x2000
	s_nop 0
	global_load_lds_dwordx4 v[216:217], off
	v_lshl_add_u64 v[216:217], s[36:37], 0, v[164:165]
	s_mov_b32 m0, s15
	s_nop 0
	global_load_lds_dwordx4 v[216:217], off
	s_mov_b32 m0, s38
	s_nop 0
	global_load_lds_dwordx4 v[226:227], off
	s_waitcnt vmcnt(8)
	s_waitcnt lgkmcnt(0)
	s_setprio 1
	s_barrier
	v_mfma_f32_16x16x32_bf16 v[64:67], v[132:135], v[174:177], v[64:67]
	v_mfma_f32_16x16x32_bf16 v[60:63], v[140:143], v[174:177], v[60:63]
	v_mfma_f32_16x16x32_bf16 v[48:51], v[132:135], v[188:191], v[48:51]
	v_mfma_f32_16x16x32_bf16 v[44:47], v[140:143], v[188:191], v[44:47]
	v_mfma_f32_16x16x32_bf16 v[32:35], v[132:135], v[196:199], v[32:35]
	v_mfma_f32_16x16x32_bf16 v[28:31], v[140:143], v[196:199], v[28:31]
	v_mfma_f32_16x16x32_bf16 v[16:19], v[132:135], v[204:207], v[16:19]
	v_mfma_f32_16x16x32_bf16 v[12:15], v[140:143], v[204:207], v[12:15]
	v_mfma_f32_16x16x32_bf16 v[64:67], v[136:139], v[178:181], v[64:67]
	v_mfma_f32_16x16x32_bf16 v[60:63], v[144:147], v[178:181], v[60:63]
	v_mfma_f32_16x16x32_bf16 v[48:51], v[136:139], v[192:195], v[48:51]
	v_mfma_f32_16x16x32_bf16 v[44:47], v[144:147], v[192:195], v[44:47]
	v_mfma_f32_16x16x32_bf16 v[32:35], v[136:139], v[200:203], v[32:35]
	v_mfma_f32_16x16x32_bf16 v[28:31], v[144:147], v[200:203], v[28:31]
	v_mfma_f32_16x16x32_bf16 v[16:19], v[136:139], v[208:211], v[16:19]
	v_mfma_f32_16x16x32_bf16 v[12:15], v[144:147], v[208:211], v[12:15]
	v_mfma_f32_16x16x32_bf16 v[56:59], v[148:151], v[174:177], v[56:59]
	v_mfma_f32_16x16x32_bf16 v[52:55], v[156:159], v[174:177], v[52:55]
	v_mfma_f32_16x16x32_bf16 v[40:43], v[148:151], v[188:191], v[40:43]
	v_mfma_f32_16x16x32_bf16 v[36:39], v[156:159], v[188:191], v[36:39]
	v_mfma_f32_16x16x32_bf16 v[24:27], v[148:151], v[196:199], v[24:27]
	v_mfma_f32_16x16x32_bf16 v[20:23], v[156:159], v[196:199], v[20:23]
	v_mfma_f32_16x16x32_bf16 v[8:11], v[148:151], v[204:207], v[8:11]
	v_mfma_f32_16x16x32_bf16 v[4:7], v[156:159], v[204:207], v[4:7]
	v_mfma_f32_16x16x32_bf16 v[56:59], v[152:155], v[178:181], v[56:59]
	v_mfma_f32_16x16x32_bf16 v[52:55], v[170:173], v[178:181], v[52:55]
	v_mfma_f32_16x16x32_bf16 v[40:43], v[152:155], v[192:195], v[40:43]
	v_mfma_f32_16x16x32_bf16 v[36:39], v[170:173], v[192:195], v[36:39]
	v_mfma_f32_16x16x32_bf16 v[24:27], v[152:155], v[200:203], v[24:27]
	v_mfma_f32_16x16x32_bf16 v[20:23], v[170:173], v[200:203], v[20:23]
	v_mfma_f32_16x16x32_bf16 v[8:11], v[152:155], v[208:211], v[8:11]
	v_mfma_f32_16x16x32_bf16 v[4:7], v[170:173], v[208:211], v[4:7]
	s_setprio 0
	s_barrier
	s_add_i32 s81, 0, 0x18000
	s_add_i32 s83, 0, 0x1c000
	v_add_u32_e32 v144, s81, v182
	v_add_u32_e32 v170, s83, v182
	ds_read_b128 v[132:135], v144
	ds_read_b128 v[136:139], v144 offset:1024
	ds_read_b128 v[140:143], v144 offset:2048
	ds_read_b128 v[144:147], v144 offset:3072
	ds_read_b128 v[148:151], v170
	ds_read_b128 v[152:155], v170 offset:1024
	ds_read_b128 v[156:159], v170 offset:2048
	ds_read_b128 v[170:173], v170 offset:3072
	s_add_u32 s36, s36, 0x80000
	s_addc_u32 s37, s37, 0
	s_mov_b32 m0, s39
	v_lshl_add_u64 v[228:229], s[36:37], 0, v[164:165]
	ds_read_b128 v[174:177], v186 offset:32768
	ds_read_b128 v[178:181], v186 offset:33792
	ds_read_b128 v[188:191], v186 offset:34816
	ds_read_b128 v[192:195], v186 offset:35840
	ds_read_b128 v[196:199], v186 offset:36864
	ds_read_b128 v[200:203], v186 offset:37888
	ds_read_b128 v[204:207], v186 offset:38912
	ds_read_b128 v[208:211], v186 offset:39936
	global_load_lds_dwordx4 v[228:229], off
	v_lshl_add_u64 v[228:229], s[36:37], 0, v[160:161]
	s_mov_b32 m0, s43
	s_nop 0
	global_load_lds_dwordx4 v[228:229], off
	s_waitcnt vmcnt(8)
	s_waitcnt lgkmcnt(0)
	s_setprio 1
	s_barrier
	v_mfma_f32_16x16x32_bf16 v[128:131], v[132:135], v[174:177], v[128:131]
	v_mfma_f32_16x16x32_bf16 v[124:127], v[140:143], v[174:177], v[124:127]
	v_mfma_f32_16x16x32_bf16 v[112:115], v[132:135], v[188:191], v[112:115]
	v_mfma_f32_16x16x32_bf16 v[108:111], v[140:143], v[188:191], v[108:111]
	v_mfma_f32_16x16x32_bf16 v[96:99], v[132:135], v[196:199], v[96:99]
	v_mfma_f32_16x16x32_bf16 v[92:95], v[140:143], v[196:199], v[92:95]
	v_mfma_f32_16x16x32_bf16 v[80:83], v[132:135], v[204:207], v[80:83]
	v_mfma_f32_16x16x32_bf16 v[76:79], v[140:143], v[204:207], v[76:79]
	v_mfma_f32_16x16x32_bf16 v[128:131], v[136:139], v[178:181], v[128:131]
	v_mfma_f32_16x16x32_bf16 v[124:127], v[144:147], v[178:181], v[124:127]
	v_mfma_f32_16x16x32_bf16 v[112:115], v[136:139], v[192:195], v[112:115]
	v_mfma_f32_16x16x32_bf16 v[108:111], v[144:147], v[192:195], v[108:111]
	v_mfma_f32_16x16x32_bf16 v[96:99], v[136:139], v[200:203], v[96:99]
	v_mfma_f32_16x16x32_bf16 v[92:95], v[144:147], v[200:203], v[92:95]
	v_mfma_f32_16x16x32_bf16 v[80:83], v[136:139], v[208:211], v[80:83]
	v_mfma_f32_16x16x32_bf16 v[76:79], v[144:147], v[208:211], v[76:79]
	v_mfma_f32_16x16x32_bf16 v[120:123], v[148:151], v[174:177], v[120:123]
	v_mfma_f32_16x16x32_bf16 v[116:119], v[156:159], v[174:177], v[116:119]
	v_mfma_f32_16x16x32_bf16 v[104:107], v[148:151], v[188:191], v[104:107]
	v_mfma_f32_16x16x32_bf16 v[100:103], v[156:159], v[188:191], v[100:103]
	v_mfma_f32_16x16x32_bf16 v[88:91], v[148:151], v[196:199], v[88:91]
	v_mfma_f32_16x16x32_bf16 v[84:87], v[156:159], v[196:199], v[84:87]
	v_mfma_f32_16x16x32_bf16 v[72:75], v[148:151], v[204:207], v[72:75]
	v_mfma_f32_16x16x32_bf16 v[68:71], v[156:159], v[204:207], v[68:71]
	v_mfma_f32_16x16x32_bf16 v[120:123], v[152:155], v[178:181], v[120:123]
	v_mfma_f32_16x16x32_bf16 v[116:119], v[170:173], v[178:181], v[116:119]
	v_mfma_f32_16x16x32_bf16 v[104:107], v[152:155], v[192:195], v[104:107]
	v_mfma_f32_16x16x32_bf16 v[100:103], v[170:173], v[192:195], v[100:103]
	v_mfma_f32_16x16x32_bf16 v[88:91], v[152:155], v[200:203], v[88:91]
	v_mfma_f32_16x16x32_bf16 v[84:87], v[170:173], v[200:203], v[84:87]
	v_mfma_f32_16x16x32_bf16 v[72:75], v[152:155], v[208:211], v[72:75]
	v_mfma_f32_16x16x32_bf16 v[68:71], v[170:173], v[208:211], v[68:71]
	s_setprio 0
	s_barrier
	s_add_i32 s36, s81, s0
	v_lshl_add_u64 v[212:213], v[212:213], 0, s[70:71]
	s_mov_b32 m0, s36
	ds_read_b128 v[174:177], v186 offset:49152
	ds_read_b128 v[178:181], v186 offset:50176
	ds_read_b128 v[188:191], v186 offset:51200
	ds_read_b128 v[192:195], v186 offset:52224
	ds_read_b128 v[196:199], v186 offset:53248
	ds_read_b128 v[200:203], v186 offset:54272
	ds_read_b128 v[204:207], v186 offset:55296
	ds_read_b128 v[208:211], v186 offset:56320
	global_load_lds_dwordx4 v[212:213], off
	s_add_i32 m0, s36, 0x2000
	s_add_u32 s34, s34, 0x80080
	v_lshl_add_u64 v[212:213], v[214:215], 0, s[70:71]
	s_addc_u32 s35, s35, 0
	s_add_i32 s36, s83, s0
	global_load_lds_dwordx4 v[212:213], off
	v_lshl_add_u64 v[212:213], s[34:35], 0, v[162:163]
	s_mov_b32 m0, s36
	s_nop 0
	global_load_lds_dwordx4 v[212:213], off
	v_lshl_add_u64 v[212:213], s[34:35], 0, v[0:1]
	s_add_i32 m0, s36, 0x2000
	s_nop 0
	global_load_lds_dwordx4 v[212:213], off
	v_lshl_add_u64 v[212:213], v[216:217], 0, s[70:71]
	s_mov_b32 m0, s47
	s_nop 0
	global_load_lds_dwordx4 v[212:213], off
	v_lshl_add_u64 v[212:213], v[226:227], 0, s[70:71]
	s_mov_b32 m0, s51
	s_nop 0
	global_load_lds_dwordx4 v[212:213], off
	s_waitcnt vmcnt(8)
	s_waitcnt lgkmcnt(0)
	s_setprio 1
	s_barrier
	v_mfma_f32_16x16x32_bf16 v[64:67], v[132:135], v[174:177], v[64:67]
	v_mfma_f32_16x16x32_bf16 v[60:63], v[140:143], v[174:177], v[60:63]
	v_mfma_f32_16x16x32_bf16 v[48:51], v[132:135], v[188:191], v[48:51]
	v_mfma_f32_16x16x32_bf16 v[44:47], v[140:143], v[188:191], v[44:47]
	v_mfma_f32_16x16x32_bf16 v[32:35], v[132:135], v[196:199], v[32:35]
	v_mfma_f32_16x16x32_bf16 v[28:31], v[140:143], v[196:199], v[28:31]
	v_mfma_f32_16x16x32_bf16 v[16:19], v[132:135], v[204:207], v[16:19]
	v_mfma_f32_16x16x32_bf16 v[12:15], v[140:143], v[204:207], v[12:15]
	v_mfma_f32_16x16x32_bf16 v[64:67], v[136:139], v[178:181], v[64:67]
	v_mfma_f32_16x16x32_bf16 v[60:63], v[144:147], v[178:181], v[60:63]
	v_mfma_f32_16x16x32_bf16 v[48:51], v[136:139], v[192:195], v[48:51]
	v_mfma_f32_16x16x32_bf16 v[44:47], v[144:147], v[192:195], v[44:47]
	v_mfma_f32_16x16x32_bf16 v[32:35], v[136:139], v[200:203], v[32:35]
	v_mfma_f32_16x16x32_bf16 v[28:31], v[144:147], v[200:203], v[28:31]
	v_mfma_f32_16x16x32_bf16 v[16:19], v[136:139], v[208:211], v[16:19]
	v_mfma_f32_16x16x32_bf16 v[12:15], v[144:147], v[208:211], v[12:15]
	v_mfma_f32_16x16x32_bf16 v[56:59], v[148:151], v[174:177], v[56:59]
	v_mfma_f32_16x16x32_bf16 v[52:55], v[156:159], v[174:177], v[52:55]
	v_mfma_f32_16x16x32_bf16 v[40:43], v[148:151], v[188:191], v[40:43]
	v_mfma_f32_16x16x32_bf16 v[36:39], v[156:159], v[188:191], v[36:39]
	v_mfma_f32_16x16x32_bf16 v[24:27], v[148:151], v[196:199], v[24:27]
	v_mfma_f32_16x16x32_bf16 v[20:23], v[156:159], v[196:199], v[20:23]
	v_mfma_f32_16x16x32_bf16 v[8:11], v[148:151], v[204:207], v[8:11]
	v_mfma_f32_16x16x32_bf16 v[4:7], v[156:159], v[204:207], v[4:7]
	v_mfma_f32_16x16x32_bf16 v[56:59], v[152:155], v[178:181], v[56:59]
	v_mfma_f32_16x16x32_bf16 v[52:55], v[170:173], v[178:181], v[52:55]
	v_mfma_f32_16x16x32_bf16 v[40:43], v[152:155], v[192:195], v[40:43]
	v_mfma_f32_16x16x32_bf16 v[36:39], v[170:173], v[192:195], v[36:39]
	v_mfma_f32_16x16x32_bf16 v[24:27], v[152:155], v[200:203], v[24:27]
	v_mfma_f32_16x16x32_bf16 v[20:23], v[170:173], v[200:203], v[20:23]
	v_mfma_f32_16x16x32_bf16 v[8:11], v[152:155], v[208:211], v[8:11]
	v_mfma_f32_16x16x32_bf16 v[4:7], v[170:173], v[208:211], v[4:7]
	s_setprio 0
	s_barrier
	s_add_i32 s75, s75, 2
	s_add_u32 s30, s30, 0x100
	s_addc_u32 s31, s31, 0
	s_add_u32 s69, s69, 0x100
	s_addc_u32 s74, s74, 0
	s_cmp_gt_u32 s75, 29
	s_cbranch_scc0 .LBB0_975
	s_and_b64 vcc, exec, s[20:21]
	s_cbranch_vccz .LBB0_978
	s_barrier

.LBB0_1067:
	s_add_u32 s34, s26, s12
	s_addc_u32 s35, s27, s13
	s_add_u32 s34, s34, 0x100
	s_addc_u32 s35, s35, 0
	s_add_u32 s83, s42, s12
	s_addc_u32 s92, s75, s13
	s_add_i32 s93, 0, 0x10000
	s_cmpk_eq_i32 s12, 0xf00
	s_cselect_b32 s37, s25, s35
	s_cselect_b32 s36, s81, s34
	s_cselect_b32 s35, s23, s92
	s_cselect_b32 s34, s84, s83
	s_add_i32 s83, 0, 0x14000
	v_add_u32_e32 v148, s93, v189
	v_add_u32_e32 v176, s83, v189
	ds_read_b128 v[136:139], v148
	ds_read_b128 v[140:143], v148 offset:1024
	ds_read_b128 v[144:147], v148 offset:2048
	ds_read_b128 v[148:151], v148 offset:3072
	ds_read_b128 v[152:155], v176
	ds_read_b128 v[156:159], v176 offset:1024
	ds_read_b128 v[160:163], v176 offset:2048
	ds_read_b128 v[176:179], v176 offset:3072
	v_lshl_add_u64 v[184:185], v[132:133], 0, s[12:13]
	s_add_i32 m0, s39, 0xc000
	ds_read_b128 v[180:183], v192
	ds_read_b128 v[194:197], v192 offset:1024
	ds_read_b128 v[198:201], v192 offset:2048
	ds_read_b128 v[202:205], v192 offset:3072
	ds_read_b128 v[206:209], v192 offset:4096
	ds_read_b128 v[210:213], v192 offset:5120
	ds_read_b128 v[214:217], v192 offset:6144
	ds_read_b128 v[226:229], v192 offset:7168
	global_load_lds_dwordx4 v[184:185], off
	v_lshl_add_u64 v[184:185], v[134:135], 0, s[12:13]
	s_add_i32 m0, s39, 0xe000
	s_nop 0
	global_load_lds_dwordx4 v[184:185], off
	s_waitcnt vmcnt(8)
	s_waitcnt lgkmcnt(0)
	s_setprio 1
	s_barrier
	v_mfma_f32_16x16x32_bf16 v[8:11], v[136:139], v[180:183], v[8:11]
	v_mfma_f32_16x16x32_bf16 v[128:131], v[144:147], v[180:183], v[128:131]
	v_mfma_f32_16x16x32_bf16 v[124:127], v[136:139], v[198:201], v[124:127]
	v_mfma_f32_16x16x32_bf16 v[120:123], v[144:147], v[198:201], v[120:123]
	v_mfma_f32_16x16x32_bf16 v[116:119], v[136:139], v[206:209], v[116:119]
	v_mfma_f32_16x16x32_bf16 v[112:115], v[144:147], v[206:209], v[112:115]
	v_mfma_f32_16x16x32_bf16 v[108:111], v[136:139], v[214:217], v[108:111]
	v_mfma_f32_16x16x32_bf16 v[104:107], v[144:147], v[214:217], v[104:107]
	v_mfma_f32_16x16x32_bf16 v[8:11], v[140:143], v[194:197], v[8:11]
	v_mfma_f32_16x16x32_bf16 v[128:131], v[148:151], v[194:197], v[128:131]
	v_mfma_f32_16x16x32_bf16 v[124:127], v[140:143], v[202:205], v[124:127]
	v_mfma_f32_16x16x32_bf16 v[120:123], v[148:151], v[202:205], v[120:123]
	v_mfma_f32_16x16x32_bf16 v[116:119], v[140:143], v[210:213], v[116:119]
	v_mfma_f32_16x16x32_bf16 v[112:115], v[148:151], v[210:213], v[112:115]
	v_mfma_f32_16x16x32_bf16 v[108:111], v[140:143], v[226:229], v[108:111]
	v_mfma_f32_16x16x32_bf16 v[104:107], v[148:151], v[226:229], v[104:107]
	v_mfma_f32_16x16x32_bf16 v[100:103], v[152:155], v[180:183], v[100:103]
	v_mfma_f32_16x16x32_bf16 v[96:99], v[160:163], v[180:183], v[96:99]
	v_mfma_f32_16x16x32_bf16 v[92:95], v[152:155], v[198:201], v[92:95]
	v_mfma_f32_16x16x32_bf16 v[88:91], v[160:163], v[198:201], v[88:91]
	v_mfma_f32_16x16x32_bf16 v[84:87], v[152:155], v[206:209], v[84:87]
	v_mfma_f32_16x16x32_bf16 v[80:83], v[160:163], v[206:209], v[80:83]
	v_mfma_f32_16x16x32_bf16 v[76:79], v[152:155], v[214:217], v[76:79]
	v_mfma_f32_16x16x32_bf16 v[72:75], v[160:163], v[214:217], v[72:75]
	v_mfma_f32_16x16x32_bf16 v[100:103], v[156:159], v[194:197], v[100:103]
	v_mfma_f32_16x16x32_bf16 v[96:99], v[176:179], v[194:197], v[96:99]
	v_mfma_f32_16x16x32_bf16 v[92:95], v[156:159], v[202:205], v[92:95]
	v_mfma_f32_16x16x32_bf16 v[88:91], v[176:179], v[202:205], v[88:91]
	v_mfma_f32_16x16x32_bf16 v[84:87], v[156:159], v[210:213], v[84:87]
	v_mfma_f32_16x16x32_bf16 v[80:83], v[176:179], v[210:213], v[80:83]
	v_mfma_f32_16x16x32_bf16 v[76:79], v[156:159], v[226:229], v[76:79]
	v_mfma_f32_16x16x32_bf16 v[72:75], v[176:179], v[226:229], v[72:75]
	s_setprio 0
	s_barrier
	s_add_i32 s92, s93, s38
	v_lshl_add_u64 v[184:185], s[34:35], 0, v[164:165]
	s_mov_b32 m0, s92
	ds_read_b128 v[180:183], v192 offset:16384
	ds_read_b128 v[194:197], v192 offset:17408
	ds_read_b128 v[198:201], v192 offset:18432
	ds_read_b128 v[202:205], v192 offset:19456
	ds_read_b128 v[206:209], v192 offset:20480
	ds_read_b128 v[210:213], v192 offset:21504
	ds_read_b128 v[214:217], v192 offset:22528
	ds_read_b128 v[226:229], v192 offset:23552
	global_load_lds_dwordx4 v[184:185], off
	s_add_i32 m0, s92, 0x2000
	s_add_u32 s92, s34, 0x80000
	v_lshl_add_u64 v[230:231], s[34:35], 0, v[168:169]
	s_addc_u32 s93, s35, 0
	s_add_i32 s83, s83, s38
	global_load_lds_dwordx4 v[230:231], off
	v_lshl_add_u64 v[232:233], s[92:93], 0, v[164:165]
	s_mov_b32 m0, s83
	v_lshl_add_u64 v[234:235], s[36:37], 0, v[166:167]
	global_load_lds_dwordx4 v[232:233], off
	v_lshl_add_u64 v[232:233], s[92:93], 0, v[168:169]
	s_add_i32 m0, s83, 0x2000
	s_nop 0
	global_load_lds_dwordx4 v[232:233], off
	v_lshl_add_u64 v[232:233], s[36:37], 0, v[0:1]
	s_mov_b32 m0, s39
	s_nop 0
	global_load_lds_dwordx4 v[232:233], off
	s_mov_b32 m0, s43
	s_nop 0
	global_load_lds_dwordx4 v[234:235], off
	s_waitcnt vmcnt(8)
	s_waitcnt lgkmcnt(0)
	s_setprio 1
	s_barrier
	v_mfma_f32_16x16x32_bf16 v[68:71], v[136:139], v[180:183], v[68:71]
	v_mfma_f32_16x16x32_bf16 v[64:67], v[144:147], v[180:183], v[64:67]
	v_mfma_f32_16x16x32_bf16 v[60:63], v[136:139], v[198:201], v[60:63]
	v_mfma_f32_16x16x32_bf16 v[56:59], v[144:147], v[198:201], v[56:59]
	v_mfma_f32_16x16x32_bf16 v[52:55], v[136:139], v[206:209], v[52:55]
	v_mfma_f32_16x16x32_bf16 v[48:51], v[144:147], v[206:209], v[48:51]
	v_mfma_f32_16x16x32_bf16 v[44:47], v[136:139], v[214:217], v[44:47]
	v_mfma_f32_16x16x32_bf16 v[40:43], v[144:147], v[214:217], v[40:43]
	v_mfma_f32_16x16x32_bf16 v[68:71], v[140:143], v[194:197], v[68:71]
	v_mfma_f32_16x16x32_bf16 v[64:67], v[148:151], v[194:197], v[64:67]
	v_mfma_f32_16x16x32_bf16 v[60:63], v[140:143], v[202:205], v[60:63]
	v_mfma_f32_16x16x32_bf16 v[56:59], v[148:151], v[202:205], v[56:59]
	v_mfma_f32_16x16x32_bf16 v[52:55], v[140:143], v[210:213], v[52:55]
	v_mfma_f32_16x16x32_bf16 v[48:51], v[148:151], v[210:213], v[48:51]
	v_mfma_f32_16x16x32_bf16 v[44:47], v[140:143], v[226:229], v[44:47]
	v_mfma_f32_16x16x32_bf16 v[40:43], v[148:151], v[226:229], v[40:43]
	v_mfma_f32_16x16x32_bf16 v[36:39], v[152:155], v[180:183], v[36:39]
	v_mfma_f32_16x16x32_bf16 v[32:35], v[160:163], v[180:183], v[32:35]
	v_mfma_f32_16x16x32_bf16 v[28:31], v[152:155], v[198:201], v[28:31]
	v_mfma_f32_16x16x32_bf16 v[24:27], v[160:163], v[198:201], v[24:27]
	v_mfma_f32_16x16x32_bf16 v[20:23], v[152:155], v[206:209], v[20:23]
	v_mfma_f32_16x16x32_bf16 v[16:19], v[160:163], v[206:209], v[16:19]
	v_mfma_f32_16x16x32_bf16 v[12:15], v[152:155], v[214:217], v[12:15]
	v_mfma_f32_16x16x32_bf16 v[4:7], v[160:163], v[214:217], v[4:7]
	v_mfma_f32_16x16x32_bf16 v[36:39], v[156:159], v[194:197], v[36:39]
	v_mfma_f32_16x16x32_bf16 v[32:35], v[176:179], v[194:197], v[32:35]
	v_mfma_f32_16x16x32_bf16 v[28:31], v[156:159], v[202:205], v[28:31]
	v_mfma_f32_16x16x32_bf16 v[24:27], v[176:179], v[202:205], v[24:27]
	v_mfma_f32_16x16x32_bf16 v[20:23], v[156:159], v[210:213], v[20:23]
	v_mfma_f32_16x16x32_bf16 v[16:19], v[176:179], v[210:213], v[16:19]
	v_mfma_f32_16x16x32_bf16 v[12:15], v[156:159], v[226:229], v[12:15]
	v_mfma_f32_16x16x32_bf16 v[4:7], v[176:179], v[226:229], v[4:7]
	s_setprio 0
	s_barrier
	s_add_i32 s83, 0, 0x18000
	s_add_i32 s92, 0, 0x1c000
	v_add_u32_e32 v148, s83, v189
	v_add_u32_e32 v176, s92, v189
	ds_read_b128 v[136:139], v148
	ds_read_b128 v[140:143], v148 offset:1024
	ds_read_b128 v[144:147], v148 offset:2048
	ds_read_b128 v[148:151], v148 offset:3072
	ds_read_b128 v[152:155], v176
	ds_read_b128 v[156:159], v176 offset:1024
	ds_read_b128 v[160:163], v176 offset:2048
	ds_read_b128 v[176:179], v176 offset:3072
	s_add_u32 s36, s36, 0x80000
	s_addc_u32 s37, s37, 0
	s_mov_b32 m0, s46
	v_lshl_add_u64 v[236:237], s[36:37], 0, v[0:1]
	ds_read_b128 v[180:183], v192 offset:32768
	ds_read_b128 v[194:197], v192 offset:33792
	ds_read_b128 v[198:201], v192 offset:34816
	ds_read_b128 v[202:205], v192 offset:35840
	ds_read_b128 v[206:209], v192 offset:36864
	ds_read_b128 v[210:213], v192 offset:37888
	ds_read_b128 v[214:217], v192 offset:38912
	ds_read_b128 v[226:229], v192 offset:39936
	global_load_lds_dwordx4 v[236:237], off
	v_lshl_add_u64 v[236:237], s[36:37], 0, v[166:167]
	s_mov_b32 m0, s47
	s_nop 0
	global_load_lds_dwordx4 v[236:237], off
	s_waitcnt vmcnt(8)
	s_waitcnt lgkmcnt(0)
	s_setprio 1
	s_barrier
	v_mfma_f32_16x16x32_bf16 v[8:11], v[136:139], v[180:183], v[8:11]
	v_mfma_f32_16x16x32_bf16 v[128:131], v[144:147], v[180:183], v[128:131]
	v_mfma_f32_16x16x32_bf16 v[124:127], v[136:139], v[198:201], v[124:127]
	v_mfma_f32_16x16x32_bf16 v[120:123], v[144:147], v[198:201], v[120:123]
	v_mfma_f32_16x16x32_bf16 v[116:119], v[136:139], v[206:209], v[116:119]
	v_mfma_f32_16x16x32_bf16 v[112:115], v[144:147], v[206:209], v[112:115]
	v_mfma_f32_16x16x32_bf16 v[108:111], v[136:139], v[214:217], v[108:111]
	v_mfma_f32_16x16x32_bf16 v[104:107], v[144:147], v[214:217], v[104:107]
	v_mfma_f32_16x16x32_bf16 v[8:11], v[140:143], v[194:197], v[8:11]
	v_mfma_f32_16x16x32_bf16 v[128:131], v[148:151], v[194:197], v[128:131]
	v_mfma_f32_16x16x32_bf16 v[124:127], v[140:143], v[202:205], v[124:127]
	v_mfma_f32_16x16x32_bf16 v[120:123], v[148:151], v[202:205], v[120:123]
	v_mfma_f32_16x16x32_bf16 v[116:119], v[140:143], v[210:213], v[116:119]
	v_mfma_f32_16x16x32_bf16 v[112:115], v[148:151], v[210:213], v[112:115]
	v_mfma_f32_16x16x32_bf16 v[108:111], v[140:143], v[226:229], v[108:111]
	v_mfma_f32_16x16x32_bf16 v[104:107], v[148:151], v[226:229], v[104:107]
	v_mfma_f32_16x16x32_bf16 v[100:103], v[152:155], v[180:183], v[100:103]
	v_mfma_f32_16x16x32_bf16 v[96:99], v[160:163], v[180:183], v[96:99]
	v_mfma_f32_16x16x32_bf16 v[92:95], v[152:155], v[198:201], v[92:95]
	v_mfma_f32_16x16x32_bf16 v[88:91], v[160:163], v[198:201], v[88:91]
	v_mfma_f32_16x16x32_bf16 v[84:87], v[152:155], v[206:209], v[84:87]
	v_mfma_f32_16x16x32_bf16 v[80:83], v[160:163], v[206:209], v[80:83]
	v_mfma_f32_16x16x32_bf16 v[76:79], v[152:155], v[214:217], v[76:79]
	v_mfma_f32_16x16x32_bf16 v[72:75], v[160:163], v[214:217], v[72:75]
	v_mfma_f32_16x16x32_bf16 v[100:103], v[156:159], v[194:197], v[100:103]
	v_mfma_f32_16x16x32_bf16 v[96:99], v[176:179], v[194:197], v[96:99]
	v_mfma_f32_16x16x32_bf16 v[92:95], v[156:159], v[202:205], v[92:95]
	v_mfma_f32_16x16x32_bf16 v[88:91], v[176:179], v[202:205], v[88:91]
	v_mfma_f32_16x16x32_bf16 v[84:87], v[156:159], v[210:213], v[84:87]
	v_mfma_f32_16x16x32_bf16 v[80:83], v[176:179], v[210:213], v[80:83]
	v_mfma_f32_16x16x32_bf16 v[76:79], v[156:159], v[226:229], v[76:79]
	v_mfma_f32_16x16x32_bf16 v[72:75], v[176:179], v[226:229], v[72:75]
	s_setprio 0
	s_barrier
	s_add_i32 s36, s83, s38
	v_lshl_add_u64 v[184:185], v[184:185], 0, s[70:71]
	s_mov_b32 m0, s36
	ds_read_b128 v[180:183], v192 offset:49152
	ds_read_b128 v[194:197], v192 offset:50176
	ds_read_b128 v[198:201], v192 offset:51200
	ds_read_b128 v[202:205], v192 offset:52224
	ds_read_b128 v[206:209], v192 offset:53248
	ds_read_b128 v[210:213], v192 offset:54272
	ds_read_b128 v[214:217], v192 offset:55296
	ds_read_b128 v[226:229], v192 offset:56320
	global_load_lds_dwordx4 v[184:185], off
	s_add_i32 m0, s36, 0x2000
	s_add_u32 s34, s34, 0x80080
	v_lshl_add_u64 v[184:185], v[230:231], 0, s[70:71]
	s_addc_u32 s35, s35, 0
	s_add_i32 s36, s92, s38
	global_load_lds_dwordx4 v[184:185], off
	v_lshl_add_u64 v[184:185], s[34:35], 0, v[164:165]
	s_mov_b32 m0, s36
	s_nop 0
	global_load_lds_dwordx4 v[184:185], off
	v_lshl_add_u64 v[184:185], s[34:35], 0, v[168:169]
	s_add_i32 m0, s36, 0x2000
	s_nop 0
	global_load_lds_dwordx4 v[184:185], off
	v_lshl_add_u64 v[184:185], v[232:233], 0, s[70:71]
	s_mov_b32 m0, s51
	s_nop 0
	global_load_lds_dwordx4 v[184:185], off
	v_lshl_add_u64 v[184:185], v[234:235], 0, s[70:71]
	s_mov_b32 m0, s52
	s_nop 0
	global_load_lds_dwordx4 v[184:185], off
	s_waitcnt vmcnt(8)
	s_waitcnt lgkmcnt(0)
	s_setprio 1
	s_barrier
	v_mfma_f32_16x16x32_bf16 v[68:71], v[136:139], v[180:183], v[68:71]
	v_mfma_f32_16x16x32_bf16 v[64:67], v[144:147], v[180:183], v[64:67]
	v_mfma_f32_16x16x32_bf16 v[60:63], v[136:139], v[198:201], v[60:63]
	v_mfma_f32_16x16x32_bf16 v[56:59], v[144:147], v[198:201], v[56:59]
	v_mfma_f32_16x16x32_bf16 v[52:55], v[136:139], v[206:209], v[52:55]
	v_mfma_f32_16x16x32_bf16 v[48:51], v[144:147], v[206:209], v[48:51]
	v_mfma_f32_16x16x32_bf16 v[44:47], v[136:139], v[214:217], v[44:47]
	v_mfma_f32_16x16x32_bf16 v[40:43], v[144:147], v[214:217], v[40:43]
	v_mfma_f32_16x16x32_bf16 v[68:71], v[140:143], v[194:197], v[68:71]
	v_mfma_f32_16x16x32_bf16 v[64:67], v[148:151], v[194:197], v[64:67]
	v_mfma_f32_16x16x32_bf16 v[60:63], v[140:143], v[202:205], v[60:63]
	v_mfma_f32_16x16x32_bf16 v[56:59], v[148:151], v[202:205], v[56:59]
	v_mfma_f32_16x16x32_bf16 v[52:55], v[140:143], v[210:213], v[52:55]
	v_mfma_f32_16x16x32_bf16 v[48:51], v[148:151], v[210:213], v[48:51]
	v_mfma_f32_16x16x32_bf16 v[44:47], v[140:143], v[226:229], v[44:47]
	v_mfma_f32_16x16x32_bf16 v[40:43], v[148:151], v[226:229], v[40:43]
	v_mfma_f32_16x16x32_bf16 v[36:39], v[152:155], v[180:183], v[36:39]
	v_mfma_f32_16x16x32_bf16 v[32:35], v[160:163], v[180:183], v[32:35]
	v_mfma_f32_16x16x32_bf16 v[28:31], v[152:155], v[198:201], v[28:31]
	v_mfma_f32_16x16x32_bf16 v[24:27], v[160:163], v[198:201], v[24:27]
	v_mfma_f32_16x16x32_bf16 v[20:23], v[152:155], v[206:209], v[20:23]
	v_mfma_f32_16x16x32_bf16 v[16:19], v[160:163], v[206:209], v[16:19]
	v_mfma_f32_16x16x32_bf16 v[12:15], v[152:155], v[214:217], v[12:15]
	v_mfma_f32_16x16x32_bf16 v[4:7], v[160:163], v[214:217], v[4:7]
	v_mfma_f32_16x16x32_bf16 v[36:39], v[156:159], v[194:197], v[36:39]
	v_mfma_f32_16x16x32_bf16 v[32:35], v[176:179], v[194:197], v[32:35]
	v_mfma_f32_16x16x32_bf16 v[28:31], v[156:159], v[202:205], v[28:31]
	v_mfma_f32_16x16x32_bf16 v[24:27], v[176:179], v[202:205], v[24:27]
	v_mfma_f32_16x16x32_bf16 v[20:23], v[156:159], v[210:213], v[20:23]
	v_mfma_f32_16x16x32_bf16 v[16:19], v[176:179], v[210:213], v[16:19]
	v_mfma_f32_16x16x32_bf16 v[12:15], v[156:159], v[226:229], v[12:15]
	v_mfma_f32_16x16x32_bf16 v[4:7], v[176:179], v[226:229], v[4:7]
	s_setprio 0
	s_barrier
	s_add_i32 s85, s85, 2
	s_add_u32 s12, s12, 0x100
	s_addc_u32 s13, s13, 0
	s_cmp_gt_u32 s85, 29
	s_cbranch_scc0 .LBB0_1067
	s_and_b64 vcc, exec, s[20:21]
	s_cbranch_vccz .LBB0_1070
	s_barrier

.LBB0_1205:
	s_add_u32 s24, s22, 0x100
	s_addc_u32 s25, s23, 0
	s_add_i32 s67, 0, 0x10000
	s_cmpk_eq_i32 s66, 0x54
	s_cselect_b32 s29, s9, s25
	s_cselect_b32 s28, s8, s24
	s_cselect_b32 s27, s21, s54
	s_cselect_b32 s26, s20, s52
	s_add_i32 s69, 0, 0x14000
	v_add_u32_e32 v144, s67, v182
	v_add_u32_e32 v170, s69, v182
	ds_read_b128 v[132:135], v144
	ds_read_b128 v[136:139], v144 offset:1024
	ds_read_b128 v[140:143], v144 offset:2048
	ds_read_b128 v[144:147], v144 offset:3072
	ds_read_b128 v[148:151], v170
	ds_read_b128 v[152:155], v170 offset:1024
	ds_read_b128 v[156:159], v170 offset:2048
	ds_read_b128 v[170:173], v170 offset:3072
	v_lshl_add_u64 v[212:213], s[22:23], 0, v[166:167]
	s_add_i32 m0, s31, 0xc000
	ds_read_b128 v[174:177], v186
	ds_read_b128 v[178:181], v186 offset:1024
	ds_read_b128 v[188:191], v186 offset:2048
	ds_read_b128 v[192:195], v186 offset:3072
	ds_read_b128 v[196:199], v186 offset:4096
	ds_read_b128 v[200:203], v186 offset:5120
	ds_read_b128 v[204:207], v186 offset:6144
	ds_read_b128 v[208:211], v186 offset:7168
	global_load_lds_dwordx4 v[212:213], off
	v_lshl_add_u64 v[212:213], s[22:23], 0, v[168:169]
	s_add_i32 m0, s31, 0xe000
	s_nop 0
	global_load_lds_dwordx4 v[212:213], off
	s_waitcnt vmcnt(8)
	s_waitcnt lgkmcnt(0)
	s_setprio 1
	s_barrier
	v_mfma_f32_16x16x32_bf16 v[128:131], v[132:135], v[174:177], v[128:131]
	v_mfma_f32_16x16x32_bf16 v[124:127], v[140:143], v[174:177], v[124:127]
	v_mfma_f32_16x16x32_bf16 v[112:115], v[132:135], v[188:191], v[112:115]
	v_mfma_f32_16x16x32_bf16 v[108:111], v[140:143], v[188:191], v[108:111]
	v_mfma_f32_16x16x32_bf16 v[96:99], v[132:135], v[196:199], v[96:99]
	v_mfma_f32_16x16x32_bf16 v[92:95], v[140:143], v[196:199], v[92:95]
	v_mfma_f32_16x16x32_bf16 v[80:83], v[132:135], v[204:207], v[80:83]
	v_mfma_f32_16x16x32_bf16 v[76:79], v[140:143], v[204:207], v[76:79]
	v_mfma_f32_16x16x32_bf16 v[128:131], v[136:139], v[178:181], v[128:131]
	v_mfma_f32_16x16x32_bf16 v[124:127], v[144:147], v[178:181], v[124:127]
	v_mfma_f32_16x16x32_bf16 v[112:115], v[136:139], v[192:195], v[112:115]
	v_mfma_f32_16x16x32_bf16 v[108:111], v[144:147], v[192:195], v[108:111]
	v_mfma_f32_16x16x32_bf16 v[96:99], v[136:139], v[200:203], v[96:99]
	v_mfma_f32_16x16x32_bf16 v[92:95], v[144:147], v[200:203], v[92:95]
	v_mfma_f32_16x16x32_bf16 v[80:83], v[136:139], v[208:211], v[80:83]
	v_mfma_f32_16x16x32_bf16 v[76:79], v[144:147], v[208:211], v[76:79]
	v_mfma_f32_16x16x32_bf16 v[120:123], v[148:151], v[174:177], v[120:123]
	v_mfma_f32_16x16x32_bf16 v[116:119], v[156:159], v[174:177], v[116:119]
	v_mfma_f32_16x16x32_bf16 v[104:107], v[148:151], v[188:191], v[104:107]
	v_mfma_f32_16x16x32_bf16 v[100:103], v[156:159], v[188:191], v[100:103]
	v_mfma_f32_16x16x32_bf16 v[88:91], v[148:151], v[196:199], v[88:91]
	v_mfma_f32_16x16x32_bf16 v[84:87], v[156:159], v[196:199], v[84:87]
	v_mfma_f32_16x16x32_bf16 v[72:75], v[148:151], v[204:207], v[72:75]
	v_mfma_f32_16x16x32_bf16 v[68:71], v[156:159], v[204:207], v[68:71]
	v_mfma_f32_16x16x32_bf16 v[120:123], v[152:155], v[178:181], v[120:123]
	v_mfma_f32_16x16x32_bf16 v[116:119], v[170:173], v[178:181], v[116:119]
	v_mfma_f32_16x16x32_bf16 v[104:107], v[152:155], v[192:195], v[104:107]
	v_mfma_f32_16x16x32_bf16 v[100:103], v[170:173], v[192:195], v[100:103]
	v_mfma_f32_16x16x32_bf16 v[88:91], v[152:155], v[200:203], v[88:91]
	v_mfma_f32_16x16x32_bf16 v[84:87], v[170:173], v[200:203], v[84:87]
	v_mfma_f32_16x16x32_bf16 v[72:75], v[152:155], v[208:211], v[72:75]
	v_mfma_f32_16x16x32_bf16 v[68:71], v[170:173], v[208:211], v[68:71]
	s_setprio 0
	s_barrier
	s_add_i32 s22, s67, s30
	v_lshl_add_u64 v[212:213], s[26:27], 0, v[162:163]
	s_mov_b32 m0, s22
	ds_read_b128 v[174:177], v186 offset:16384
	ds_read_b128 v[178:181], v186 offset:17408
	ds_read_b128 v[188:191], v186 offset:18432
	ds_read_b128 v[192:195], v186 offset:19456
	ds_read_b128 v[196:199], v186 offset:20480
	ds_read_b128 v[200:203], v186 offset:21504
	ds_read_b128 v[204:207], v186 offset:22528
	ds_read_b128 v[208:211], v186 offset:23552
	global_load_lds_dwordx4 v[212:213], off
	s_add_i32 m0, s22, 0x2000
	s_add_u32 s22, s26, 0x160000
	v_lshl_add_u64 v[214:215], s[26:27], 0, v[0:1]
	s_addc_u32 s23, s27, 0
	s_add_i32 s67, s69, s30
	global_load_lds_dwordx4 v[214:215], off
	v_lshl_add_u64 v[216:217], s[22:23], 0, v[162:163]
	s_mov_b32 m0, s67
	v_lshl_add_u64 v[226:227], s[28:29], 0, v[160:161]
	global_load_lds_dwordx4 v[216:217], off
	v_lshl_add_u64 v[216:217], s[22:23], 0, v[0:1]
	s_add_i32 m0, s67, 0x2000
	s_nop 0
	global_load_lds_dwordx4 v[216:217], off
	v_lshl_add_u64 v[216:217], s[28:29], 0, v[164:165]
	s_mov_b32 m0, s31
	s_nop 0
	global_load_lds_dwordx4 v[216:217], off
	s_mov_b32 m0, s34
	s_nop 0
	global_load_lds_dwordx4 v[226:227], off
	s_waitcnt vmcnt(8)
	s_waitcnt lgkmcnt(0)
	s_setprio 1
	s_barrier
	v_mfma_f32_16x16x32_bf16 v[64:67], v[132:135], v[174:177], v[64:67]
	v_mfma_f32_16x16x32_bf16 v[60:63], v[140:143], v[174:177], v[60:63]
	v_mfma_f32_16x16x32_bf16 v[48:51], v[132:135], v[188:191], v[48:51]
	v_mfma_f32_16x16x32_bf16 v[44:47], v[140:143], v[188:191], v[44:47]
	v_mfma_f32_16x16x32_bf16 v[32:35], v[132:135], v[196:199], v[32:35]
	v_mfma_f32_16x16x32_bf16 v[28:31], v[140:143], v[196:199], v[28:31]
	v_mfma_f32_16x16x32_bf16 v[16:19], v[132:135], v[204:207], v[16:19]
	v_mfma_f32_16x16x32_bf16 v[12:15], v[140:143], v[204:207], v[12:15]
	v_mfma_f32_16x16x32_bf16 v[64:67], v[136:139], v[178:181], v[64:67]
	v_mfma_f32_16x16x32_bf16 v[60:63], v[144:147], v[178:181], v[60:63]
	v_mfma_f32_16x16x32_bf16 v[48:51], v[136:139], v[192:195], v[48:51]
	v_mfma_f32_16x16x32_bf16 v[44:47], v[144:147], v[192:195], v[44:47]
	v_mfma_f32_16x16x32_bf16 v[32:35], v[136:139], v[200:203], v[32:35]
	v_mfma_f32_16x16x32_bf16 v[28:31], v[144:147], v[200:203], v[28:31]
	v_mfma_f32_16x16x32_bf16 v[16:19], v[136:139], v[208:211], v[16:19]
	v_mfma_f32_16x16x32_bf16 v[12:15], v[144:147], v[208:211], v[12:15]
	v_mfma_f32_16x16x32_bf16 v[56:59], v[148:151], v[174:177], v[56:59]
	v_mfma_f32_16x16x32_bf16 v[52:55], v[156:159], v[174:177], v[52:55]
	v_mfma_f32_16x16x32_bf16 v[40:43], v[148:151], v[188:191], v[40:43]
	v_mfma_f32_16x16x32_bf16 v[36:39], v[156:159], v[188:191], v[36:39]
	v_mfma_f32_16x16x32_bf16 v[24:27], v[148:151], v[196:199], v[24:27]
	v_mfma_f32_16x16x32_bf16 v[20:23], v[156:159], v[196:199], v[20:23]
	v_mfma_f32_16x16x32_bf16 v[8:11], v[148:151], v[204:207], v[8:11]
	v_mfma_f32_16x16x32_bf16 v[4:7], v[156:159], v[204:207], v[4:7]
	v_mfma_f32_16x16x32_bf16 v[56:59], v[152:155], v[178:181], v[56:59]
	v_mfma_f32_16x16x32_bf16 v[52:55], v[170:173], v[178:181], v[52:55]
	v_mfma_f32_16x16x32_bf16 v[40:43], v[152:155], v[192:195], v[40:43]
	v_mfma_f32_16x16x32_bf16 v[36:39], v[170:173], v[192:195], v[36:39]
	v_mfma_f32_16x16x32_bf16 v[24:27], v[152:155], v[200:203], v[24:27]
	v_mfma_f32_16x16x32_bf16 v[20:23], v[170:173], v[200:203], v[20:23]
	v_mfma_f32_16x16x32_bf16 v[8:11], v[152:155], v[208:211], v[8:11]
	v_mfma_f32_16x16x32_bf16 v[4:7], v[170:173], v[208:211], v[4:7]
	s_setprio 0
	s_barrier
	s_add_i32 s67, 0, 0x18000
	s_add_i32 s69, 0, 0x1c000
	v_add_u32_e32 v144, s67, v182
	v_add_u32_e32 v170, s69, v182
	ds_read_b128 v[132:135], v144
	ds_read_b128 v[136:139], v144 offset:1024
	ds_read_b128 v[140:143], v144 offset:2048
	ds_read_b128 v[144:147], v144 offset:3072
	ds_read_b128 v[148:151], v170
	ds_read_b128 v[152:155], v170 offset:1024
	ds_read_b128 v[156:159], v170 offset:2048
	ds_read_b128 v[170:173], v170 offset:3072
	s_add_u32 s22, s28, 0x160000
	s_addc_u32 s23, s29, 0
	s_mov_b32 m0, s35
	v_lshl_add_u64 v[228:229], s[22:23], 0, v[164:165]
	ds_read_b128 v[174:177], v186 offset:32768
	ds_read_b128 v[178:181], v186 offset:33792
	ds_read_b128 v[188:191], v186 offset:34816
	ds_read_b128 v[192:195], v186 offset:35840
	ds_read_b128 v[196:199], v186 offset:36864
	ds_read_b128 v[200:203], v186 offset:37888
	ds_read_b128 v[204:207], v186 offset:38912
	ds_read_b128 v[208:211], v186 offset:39936
	global_load_lds_dwordx4 v[228:229], off
	v_lshl_add_u64 v[228:229], s[22:23], 0, v[160:161]
	s_mov_b32 m0, s36
	s_nop 0
	global_load_lds_dwordx4 v[228:229], off
	s_waitcnt vmcnt(8)
	s_waitcnt lgkmcnt(0)
	s_setprio 1
	s_barrier
	v_mfma_f32_16x16x32_bf16 v[128:131], v[132:135], v[174:177], v[128:131]
	v_mfma_f32_16x16x32_bf16 v[124:127], v[140:143], v[174:177], v[124:127]
	v_mfma_f32_16x16x32_bf16 v[112:115], v[132:135], v[188:191], v[112:115]
	v_mfma_f32_16x16x32_bf16 v[108:111], v[140:143], v[188:191], v[108:111]
	v_mfma_f32_16x16x32_bf16 v[96:99], v[132:135], v[196:199], v[96:99]
	v_mfma_f32_16x16x32_bf16 v[92:95], v[140:143], v[196:199], v[92:95]
	v_mfma_f32_16x16x32_bf16 v[80:83], v[132:135], v[204:207], v[80:83]
	v_mfma_f32_16x16x32_bf16 v[76:79], v[140:143], v[204:207], v[76:79]
	v_mfma_f32_16x16x32_bf16 v[128:131], v[136:139], v[178:181], v[128:131]
	v_mfma_f32_16x16x32_bf16 v[124:127], v[144:147], v[178:181], v[124:127]
	v_mfma_f32_16x16x32_bf16 v[112:115], v[136:139], v[192:195], v[112:115]
	v_mfma_f32_16x16x32_bf16 v[108:111], v[144:147], v[192:195], v[108:111]
	v_mfma_f32_16x16x32_bf16 v[96:99], v[136:139], v[200:203], v[96:99]
	v_mfma_f32_16x16x32_bf16 v[92:95], v[144:147], v[200:203], v[92:95]
	v_mfma_f32_16x16x32_bf16 v[80:83], v[136:139], v[208:211], v[80:83]
	v_mfma_f32_16x16x32_bf16 v[76:79], v[144:147], v[208:211], v[76:79]
	v_mfma_f32_16x16x32_bf16 v[120:123], v[148:151], v[174:177], v[120:123]
	v_mfma_f32_16x16x32_bf16 v[116:119], v[156:159], v[174:177], v[116:119]
	v_mfma_f32_16x16x32_bf16 v[104:107], v[148:151], v[188:191], v[104:107]
	v_mfma_f32_16x16x32_bf16 v[100:103], v[156:159], v[188:191], v[100:103]
	v_mfma_f32_16x16x32_bf16 v[88:91], v[148:151], v[196:199], v[88:91]
	v_mfma_f32_16x16x32_bf16 v[84:87], v[156:159], v[196:199], v[84:87]
	v_mfma_f32_16x16x32_bf16 v[72:75], v[148:151], v[204:207], v[72:75]
	v_mfma_f32_16x16x32_bf16 v[68:71], v[156:159], v[204:207], v[68:71]
	v_mfma_f32_16x16x32_bf16 v[120:123], v[152:155], v[178:181], v[120:123]
	v_mfma_f32_16x16x32_bf16 v[116:119], v[170:173], v[178:181], v[116:119]
	v_mfma_f32_16x16x32_bf16 v[104:107], v[152:155], v[192:195], v[104:107]
	v_mfma_f32_16x16x32_bf16 v[100:103], v[170:173], v[192:195], v[100:103]
	v_mfma_f32_16x16x32_bf16 v[88:91], v[152:155], v[200:203], v[88:91]
	v_mfma_f32_16x16x32_bf16 v[84:87], v[170:173], v[200:203], v[84:87]
	v_mfma_f32_16x16x32_bf16 v[72:75], v[152:155], v[208:211], v[72:75]
	v_mfma_f32_16x16x32_bf16 v[68:71], v[170:173], v[208:211], v[68:71]
	s_setprio 0
	s_barrier
	s_add_i32 s22, s67, s30
	v_lshl_add_u64 v[212:213], v[212:213], 0, s[70:71]
	s_mov_b32 m0, s22
	ds_read_b128 v[174:177], v186 offset:49152
	ds_read_b128 v[178:181], v186 offset:50176
	ds_read_b128 v[188:191], v186 offset:51200
	ds_read_b128 v[192:195], v186 offset:52224
	ds_read_b128 v[196:199], v186 offset:53248
	ds_read_b128 v[200:203], v186 offset:54272
	ds_read_b128 v[204:207], v186 offset:55296
	ds_read_b128 v[208:211], v186 offset:56320
	global_load_lds_dwordx4 v[212:213], off
	s_add_i32 m0, s22, 0x2000
	s_add_u32 s22, s26, 0x160080
	v_lshl_add_u64 v[212:213], v[214:215], 0, s[70:71]
	s_addc_u32 s23, s27, 0
	s_add_i32 s26, s69, s30
	global_load_lds_dwordx4 v[212:213], off
	v_lshl_add_u64 v[212:213], s[22:23], 0, v[162:163]
	s_mov_b32 m0, s26
	s_nop 0
	global_load_lds_dwordx4 v[212:213], off
	v_lshl_add_u64 v[212:213], s[22:23], 0, v[0:1]
	s_add_i32 m0, s26, 0x2000
	s_nop 0
	global_load_lds_dwordx4 v[212:213], off
	v_lshl_add_u64 v[212:213], v[216:217], 0, s[70:71]
	s_mov_b32 m0, s38
	s_nop 0
	global_load_lds_dwordx4 v[212:213], off
	v_lshl_add_u64 v[212:213], v[226:227], 0, s[70:71]
	s_mov_b32 m0, s39
	s_nop 0
	global_load_lds_dwordx4 v[212:213], off
	s_waitcnt vmcnt(8)
	s_waitcnt lgkmcnt(0)
	s_setprio 1
	s_barrier
	v_mfma_f32_16x16x32_bf16 v[64:67], v[132:135], v[174:177], v[64:67]
	v_mfma_f32_16x16x32_bf16 v[60:63], v[140:143], v[174:177], v[60:63]
	v_mfma_f32_16x16x32_bf16 v[48:51], v[132:135], v[188:191], v[48:51]
	v_mfma_f32_16x16x32_bf16 v[44:47], v[140:143], v[188:191], v[44:47]
	v_mfma_f32_16x16x32_bf16 v[32:35], v[132:135], v[196:199], v[32:35]
	v_mfma_f32_16x16x32_bf16 v[28:31], v[140:143], v[196:199], v[28:31]
	v_mfma_f32_16x16x32_bf16 v[16:19], v[132:135], v[204:207], v[16:19]
	v_mfma_f32_16x16x32_bf16 v[12:15], v[140:143], v[204:207], v[12:15]
	v_mfma_f32_16x16x32_bf16 v[64:67], v[136:139], v[178:181], v[64:67]
	v_mfma_f32_16x16x32_bf16 v[60:63], v[144:147], v[178:181], v[60:63]
	v_mfma_f32_16x16x32_bf16 v[48:51], v[136:139], v[192:195], v[48:51]
	v_mfma_f32_16x16x32_bf16 v[44:47], v[144:147], v[192:195], v[44:47]
	v_mfma_f32_16x16x32_bf16 v[32:35], v[136:139], v[200:203], v[32:35]
	v_mfma_f32_16x16x32_bf16 v[28:31], v[144:147], v[200:203], v[28:31]
	v_mfma_f32_16x16x32_bf16 v[16:19], v[136:139], v[208:211], v[16:19]
	v_mfma_f32_16x16x32_bf16 v[12:15], v[144:147], v[208:211], v[12:15]
	v_mfma_f32_16x16x32_bf16 v[56:59], v[148:151], v[174:177], v[56:59]
	v_mfma_f32_16x16x32_bf16 v[52:55], v[156:159], v[174:177], v[52:55]
	v_mfma_f32_16x16x32_bf16 v[40:43], v[148:151], v[188:191], v[40:43]
	v_mfma_f32_16x16x32_bf16 v[36:39], v[156:159], v[188:191], v[36:39]
	v_mfma_f32_16x16x32_bf16 v[24:27], v[148:151], v[196:199], v[24:27]
	v_mfma_f32_16x16x32_bf16 v[20:23], v[156:159], v[196:199], v[20:23]
	v_mfma_f32_16x16x32_bf16 v[8:11], v[148:151], v[204:207], v[8:11]
	v_mfma_f32_16x16x32_bf16 v[4:7], v[156:159], v[204:207], v[4:7]
	v_mfma_f32_16x16x32_bf16 v[56:59], v[152:155], v[178:181], v[56:59]
	v_mfma_f32_16x16x32_bf16 v[52:55], v[170:173], v[178:181], v[52:55]
	v_mfma_f32_16x16x32_bf16 v[40:43], v[152:155], v[192:195], v[40:43]
	v_mfma_f32_16x16x32_bf16 v[36:39], v[170:173], v[192:195], v[36:39]
	v_mfma_f32_16x16x32_bf16 v[24:27], v[152:155], v[200:203], v[24:27]
	v_mfma_f32_16x16x32_bf16 v[20:23], v[170:173], v[200:203], v[20:23]
	v_mfma_f32_16x16x32_bf16 v[8:11], v[152:155], v[208:211], v[8:11]
	v_mfma_f32_16x16x32_bf16 v[4:7], v[170:173], v[208:211], v[4:7]
	s_setprio 0
	s_barrier
	s_add_i32 s66, s66, 2
	s_add_u32 s52, s52, 0x100
	s_addc_u32 s54, s54, 0
	s_cmpk_gt_u32 s66, 0x55
	s_mov_b64 s[22:23], s[24:25]
	s_cbranch_scc0 .LBB0_1205
	s_and_b64 vcc, exec, s[18:19]
	s_cbranch_vccz .LBB0_1208
	s_barrier
